# SwiGLU epilogue: accumulator shuffle movs removed (u,g no longer need adjacent registers)
# baseline (speedup 1.0000x reference)
.LBB0_165:
	v_ashrrev_i32_e32 v153, 31, v152
	v_lshlrev_b64 v[154:155], 6, v[152:153]
	v_lshl_add_u64 v[170:171], s[74:75], 0, v[154:155]
	s_waitcnt lgkmcnt(0)
	global_load_dwordx4 v[154:157], v[170:171], off
	global_load_dwordx4 v[162:165], v[170:171], off offset:16
	global_load_dwordx4 v[166:169], v[170:171], off offset:32
	s_nop 0
	global_load_dwordx4 v[170:173], v[170:171], off offset:48
	s_lshl_b32 s24, s24, 7
	v_mov_b32_e32 v174, v124
	v_mov_b32_e32 v124, v126
	v_mov_b32_e32 v126, v120
	v_mov_b32_e32 v175, v116
	v_mov_b32_e32 v116, v125
	v_mov_b32_e32 v125, v118
	v_mov_b32_e32 v118, v127
	v_mov_b32_e32 v127, v112
	v_mov_b32_e32 v112, v121
	v_mov_b64_e32 v[120:121], s[72:73]
	s_ashr_i32 s25, s24, 31
	v_mov_b32_e32 v176, v122
	v_mov_b32_e32 v177, v114
	v_mov_b32_e32 v114, v123
	v_mad_i64_i32 v[122:123], s[26:27], v152, s51, v[120:121]
	s_lshl_b64 s[24:25], s[24:25], 1
	v_lshl_add_u64 v[122:123], v[122:123], 0, s[24:25]
	v_lshl_add_u64 v[122:123], v[122:123], 0, s[6:7]
	s_waitcnt vmcnt(2)
	v_pk_add_f32 v[154:155], v[154:155], v[156:157]
	v_pk_add_f32 v[162:163], v[162:163], v[164:165]
	s_waitcnt vmcnt(0)
	v_pk_add_f32 v[166:167], v[166:167], v[168:169]
	v_pk_add_f32 v[170:171], v[170:171], v[172:173]
	v_pk_add_f32 v[154:155], v[154:155], v[162:163]
	v_pk_add_f32 v[166:167], v[166:167], v[170:171]
	v_mul_f32_e32 v116, v116, v117
	v_mul_f32_e32 v124, v124, v125
	v_mul_f32_e32 v118, v118, v119
	v_mul_f32_e32 v126, v126, v127
	v_pk_add_f32 v[154:155], v[154:155], v[166:167]
	v_mul_f32_e32 v174, v174, v175
	v_mul_f32_e32 v112, v112, v113
	v_mul_f32_e32 v176, v176, v177
	v_mul_f32_e32 v114, v114, v115
	v_add_f32_e32 v154, v154, v155
	v_fmamk_f32 v154, v154, 0x3a800000, v160
	v_rsq_f32_e32 v155, v154
	s_nop 0
	v_mul_f32_e32 v155, 0xbfb8aa3b, v155
	v_mul_f32_e32 v117, v155, v117
	v_mul_f32_e32 v125, v155, v125
	v_mul_f32_e32 v119, v155, v119
	v_mul_f32_e32 v127, v155, v127
	v_mul_f32_e32 v175, v155, v175
	v_mul_f32_e32 v113, v155, v113
	v_mul_f32_e32 v177, v155, v177
	v_mul_f32_e32 v115, v155, v115
	v_exp_f32_e32 v117, v117
	v_exp_f32_e32 v125, v125
	v_exp_f32_e32 v119, v119
	v_exp_f32_e32 v127, v127
	v_exp_f32_e32 v175, v175
	v_exp_f32_e32 v113, v113
	v_exp_f32_e32 v177, v177
	v_exp_f32_e32 v115, v115
	v_fma_f32 v117, v117, v154, v154
	v_fma_f32 v125, v125, v154, v154
	v_fma_f32 v119, v119, v154, v154
	v_fma_f32 v127, v127, v154, v154
	v_fma_f32 v175, v175, v154, v154
	v_fma_f32 v113, v113, v154, v154
	v_fma_f32 v177, v177, v154, v154
	v_fma_f32 v115, v115, v154, v154
	v_rcp_f32_e32 v117, v117
	v_rcp_f32_e32 v125, v125
	v_rcp_f32_e32 v119, v119
	v_rcp_f32_e32 v127, v127
	v_rcp_f32_e32 v175, v175
	v_rcp_f32_e32 v113, v113
	v_rcp_f32_e32 v177, v177
	v_rcp_f32_e32 v115, v115
	v_mul_f32_e32 v116, v116, v117
	v_mul_f32_e32 v124, v124, v125
	v_mul_f32_e32 v118, v118, v119
	v_mul_f32_e32 v126, v126, v127
	v_mul_f32_e32 v174, v174, v175
	v_mul_f32_e32 v112, v112, v113
	v_mul_f32_e32 v176, v176, v177
	v_mul_f32_e32 v114, v114, v115
	v_cvt_pk_bf16_f32 v113, v124, v118
	v_cvt_pk_bf16_f32 v115, v176, v114
	v_cvt_pk_bf16_f32 v114, v126, v112
	v_cvt_pk_bf16_f32 v112, v174, v116
	v_or_b32_e32 v126, 16, v152
	v_lshl_add_u64 v[116:117], v[122:123], 0, v[136:137]
	v_ashrrev_i32_e32 v127, 31, v126
	global_store_dwordx4 v[116:117], v[112:115], off
	s_nop 1
	v_lshlrev_b64 v[112:113], 6, v[126:127]
	v_lshl_add_u64 v[154:155], s[74:75], 0, v[112:113]
	global_load_dwordx4 v[112:115], v[154:155], off
	global_load_dwordx4 v[116:119], v[154:155], off offset:16
	global_load_dwordx4 v[122:125], v[154:155], off offset:32
	s_nop 0
	global_load_dwordx4 v[154:157], v[154:155], off offset:48
	s_waitcnt vmcnt(2)
	v_pk_add_f32 v[112:113], v[112:113], v[114:115]
	v_pk_add_f32 v[116:117], v[116:117], v[118:119]
	s_waitcnt vmcnt(0)
	v_pk_add_f32 v[122:123], v[122:123], v[124:125]
	v_pk_add_f32 v[154:155], v[154:155], v[156:157]
	v_pk_add_f32 v[112:113], v[112:113], v[116:117]
	v_pk_add_f32 v[122:123], v[122:123], v[154:155]
	v_mul_f32_e32 v109, v109, v101
	v_mul_f32_e32 v110, v110, v102
	v_mul_f32_e32 v108, v108, v100
	v_mul_f32_e32 v111, v111, v103
	v_pk_add_f32 v[112:113], v[112:113], v[122:123]
	v_mul_f32_e32 v104, v104, v96
	v_mul_f32_e32 v105, v105, v97
	v_mul_f32_e32 v106, v106, v98
	v_mul_f32_e32 v107, v107, v99
	v_add_f32_e32 v112, v112, v113
	v_fmamk_f32 v112, v112, 0x3a800000, v160
	v_rsq_f32_e32 v113, v112
	s_nop 0
	v_mul_f32_e32 v113, 0xbfb8aa3b, v113
	v_mul_f32_e32 v101, v113, v101
	v_mul_f32_e32 v102, v113, v102
	v_mul_f32_e32 v100, v113, v100
	v_mul_f32_e32 v103, v113, v103
	v_mul_f32_e32 v96, v113, v96
	v_mul_f32_e32 v97, v113, v97
	v_mul_f32_e32 v98, v113, v98
	v_mul_f32_e32 v99, v113, v99
	v_exp_f32_e32 v101, v101
	v_exp_f32_e32 v102, v102
	v_exp_f32_e32 v100, v100
	v_exp_f32_e32 v103, v103
	v_exp_f32_e32 v96, v96
	v_exp_f32_e32 v97, v97
	v_exp_f32_e32 v98, v98
	v_exp_f32_e32 v99, v99
	v_fma_f32 v101, v101, v112, v112
	v_fma_f32 v102, v102, v112, v112
	v_fma_f32 v100, v100, v112, v112
	v_fma_f32 v103, v103, v112, v112
	v_fma_f32 v96, v96, v112, v112
	v_fma_f32 v97, v97, v112, v112
	v_fma_f32 v98, v98, v112, v112
	v_fma_f32 v99, v99, v112, v112
	v_rcp_f32_e32 v101, v101
	v_rcp_f32_e32 v102, v102
	v_rcp_f32_e32 v100, v100
	v_rcp_f32_e32 v103, v103
	v_rcp_f32_e32 v96, v96
	v_rcp_f32_e32 v97, v97
	v_rcp_f32_e32 v98, v98
	v_rcp_f32_e32 v99, v99
	v_mul_f32_e32 v109, v109, v101
	v_mul_f32_e32 v110, v110, v102
	v_mul_f32_e32 v108, v108, v100
	v_mul_f32_e32 v111, v111, v103
	v_mul_f32_e32 v104, v104, v96
	v_mul_f32_e32 v105, v105, v97
	v_mul_f32_e32 v106, v106, v98
	v_mul_f32_e32 v107, v107, v99
	v_cvt_pk_bf16_f32 v96, v108, v109
	v_cvt_pk_bf16_f32 v97, v110, v111
	v_cvt_pk_bf16_f32 v98, v104, v105
	v_cvt_pk_bf16_f32 v99, v106, v107
	v_mad_i64_i32 v[112:113], s[26:27], v126, s51, v[120:121]
	v_lshl_add_u64 v[112:113], v[112:113], 0, s[24:25]
	v_lshl_add_u64 v[100:101], v[112:113], 0, s[6:7]
	v_or_b32_e32 v112, 32, v152
	v_lshl_add_u64 v[100:101], v[100:101], 0, v[136:137]
	v_ashrrev_i32_e32 v113, 31, v112
	global_store_dwordx4 v[100:101], v[96:99], off
	s_nop 1
	v_lshlrev_b64 v[96:97], 6, v[112:113]
	v_lshl_add_u64 v[108:109], s[74:75], 0, v[96:97]
	global_load_dwordx4 v[96:99], v[108:109], off
	global_load_dwordx4 v[100:103], v[108:109], off offset:16
	global_load_dwordx4 v[104:107], v[108:109], off offset:32
	s_nop 0
	global_load_dwordx4 v[108:111], v[108:109], off offset:48
	s_waitcnt vmcnt(2)
	v_pk_add_f32 v[96:97], v[96:97], v[98:99]
	v_pk_add_f32 v[100:101], v[100:101], v[102:103]
	s_waitcnt vmcnt(0)
	v_pk_add_f32 v[104:105], v[104:105], v[106:107]
	v_pk_add_f32 v[108:109], v[108:109], v[110:111]
	v_pk_add_f32 v[96:97], v[96:97], v[100:101]
	v_pk_add_f32 v[104:105], v[104:105], v[108:109]
	v_mul_f32_e32 v92, v92, v88
	v_mul_f32_e32 v93, v93, v89
	v_mul_f32_e32 v94, v94, v90
	v_mul_f32_e32 v95, v95, v91
	v_pk_add_f32 v[96:97], v[96:97], v[104:105]
	v_mul_f32_e32 v80, v80, v84
	v_mul_f32_e32 v81, v81, v85
	v_mul_f32_e32 v82, v82, v86
	v_mul_f32_e32 v83, v83, v87
	v_add_f32_e32 v96, v96, v97
	v_fmamk_f32 v96, v96, 0x3a800000, v160
	v_rsq_f32_e32 v97, v96
	s_nop 0
	v_mul_f32_e32 v97, 0xbfb8aa3b, v97
	v_mul_f32_e32 v88, v97, v88
	v_mul_f32_e32 v89, v97, v89
	v_mul_f32_e32 v90, v97, v90
	v_mul_f32_e32 v91, v97, v91
	v_mul_f32_e32 v84, v97, v84
	v_mul_f32_e32 v85, v97, v85
	v_mul_f32_e32 v86, v97, v86
	v_mul_f32_e32 v87, v97, v87
	v_exp_f32_e32 v88, v88
	v_exp_f32_e32 v89, v89
	v_exp_f32_e32 v90, v90
	v_exp_f32_e32 v91, v91
	v_exp_f32_e32 v84, v84
	v_exp_f32_e32 v85, v85
	v_exp_f32_e32 v86, v86
	v_exp_f32_e32 v87, v87
	v_fma_f32 v88, v88, v96, v96
	v_fma_f32 v89, v89, v96, v96
	v_fma_f32 v90, v90, v96, v96
	v_fma_f32 v91, v91, v96, v96
	v_fma_f32 v84, v84, v96, v96
	v_fma_f32 v85, v85, v96, v96
	v_fma_f32 v86, v86, v96, v96
	v_fma_f32 v87, v87, v96, v96
	v_rcp_f32_e32 v88, v88
	v_rcp_f32_e32 v89, v89
	v_rcp_f32_e32 v90, v90
	v_rcp_f32_e32 v91, v91
	v_rcp_f32_e32 v84, v84
	v_rcp_f32_e32 v85, v85
	v_rcp_f32_e32 v86, v86
	v_rcp_f32_e32 v87, v87
	v_mul_f32_e32 v92, v92, v88
	v_mul_f32_e32 v93, v93, v89
	v_mul_f32_e32 v94, v94, v90
	v_mul_f32_e32 v95, v95, v91
	v_mul_f32_e32 v80, v80, v84
	v_mul_f32_e32 v81, v81, v85
	v_mul_f32_e32 v82, v82, v86
	v_mul_f32_e32 v83, v83, v87
	v_cvt_pk_bf16_f32 v83, v82, v83
	v_cvt_pk_bf16_f32 v82, v80, v81
	v_cvt_pk_bf16_f32 v80, v92, v93
	v_cvt_pk_bf16_f32 v81, v94, v95
	v_mad_i64_i32 v[96:97], s[26:27], v112, s51, v[120:121]
	v_lshl_add_u64 v[84:85], v[96:97], 0, s[24:25]
	v_lshl_add_u64 v[84:85], v[84:85], 0, s[6:7]
	v_or_b32_e32 v96, 48, v152
	v_lshl_add_u64 v[84:85], v[84:85], 0, v[136:137]
	v_ashrrev_i32_e32 v97, 31, v96
	global_store_dwordx4 v[84:85], v[80:83], off
	s_nop 1
	v_lshlrev_b64 v[80:81], 6, v[96:97]
	v_lshl_add_u64 v[92:93], s[74:75], 0, v[80:81]
	global_load_dwordx4 v[80:83], v[92:93], off
	global_load_dwordx4 v[84:87], v[92:93], off offset:16
	global_load_dwordx4 v[88:91], v[92:93], off offset:32
	s_nop 0
	global_load_dwordx4 v[92:95], v[92:93], off offset:48
	s_waitcnt vmcnt(2)
	v_pk_add_f32 v[80:81], v[80:81], v[82:83]
	v_pk_add_f32 v[84:85], v[84:85], v[86:87]
	s_waitcnt vmcnt(0)
	v_pk_add_f32 v[88:89], v[88:89], v[90:91]
	v_pk_add_f32 v[92:93], v[92:93], v[94:95]
	v_pk_add_f32 v[80:81], v[80:81], v[84:85]
	v_pk_add_f32 v[88:89], v[88:89], v[92:93]
	v_mul_f32_e32 v76, v76, v72
	v_mul_f32_e32 v77, v77, v73
	v_mul_f32_e32 v78, v78, v74
	v_mul_f32_e32 v65, v65, v69
	v_pk_add_f32 v[80:81], v[80:81], v[88:89]
	v_mul_f32_e32 v66, v66, v70
	v_mul_f32_e32 v79, v79, v75
	v_mul_f32_e32 v64, v64, v68
	v_mul_f32_e32 v67, v67, v71
	v_add_f32_e32 v80, v80, v81
	v_fmamk_f32 v80, v80, 0x3a800000, v160
	v_rsq_f32_e32 v81, v80
	s_nop 0
	v_mul_f32_e32 v81, 0xbfb8aa3b, v81
	v_mul_f32_e32 v72, v81, v72
	v_mul_f32_e32 v73, v81, v73
	v_mul_f32_e32 v74, v81, v74
	v_mul_f32_e32 v69, v81, v69
	v_mul_f32_e32 v70, v81, v70
	v_mul_f32_e32 v75, v81, v75
	v_mul_f32_e32 v68, v81, v68
	v_mul_f32_e32 v71, v81, v71
	v_exp_f32_e32 v72, v72
	v_exp_f32_e32 v73, v73
	v_exp_f32_e32 v74, v74
	v_exp_f32_e32 v69, v69
	v_exp_f32_e32 v70, v70
	v_exp_f32_e32 v75, v75
	v_exp_f32_e32 v68, v68
	v_exp_f32_e32 v71, v71
	v_fma_f32 v72, v72, v80, v80
	v_fma_f32 v73, v73, v80, v80
	v_fma_f32 v74, v74, v80, v80
	v_fma_f32 v69, v69, v80, v80
	v_fma_f32 v70, v70, v80, v80
	v_fma_f32 v75, v75, v80, v80
	v_fma_f32 v68, v68, v80, v80
	v_fma_f32 v71, v71, v80, v80
	v_rcp_f32_e32 v72, v72
	v_rcp_f32_e32 v73, v73
	v_rcp_f32_e32 v74, v74
	v_rcp_f32_e32 v69, v69
	v_rcp_f32_e32 v70, v70
	v_rcp_f32_e32 v75, v75
	v_rcp_f32_e32 v68, v68
	v_rcp_f32_e32 v71, v71
	v_mul_f32_e32 v76, v76, v72
	v_mul_f32_e32 v77, v77, v73
	v_mul_f32_e32 v78, v78, v74
	v_mul_f32_e32 v65, v65, v69
	v_mul_f32_e32 v66, v66, v70
	v_mul_f32_e32 v79, v79, v75
	v_mul_f32_e32 v64, v64, v68
	v_mul_f32_e32 v67, v67, v71
	v_cvt_pk_bf16_f32 v67, v66, v67
	v_cvt_pk_bf16_f32 v66, v64, v65
	v_cvt_pk_bf16_f32 v64, v76, v77
	v_cvt_pk_bf16_f32 v65, v78, v79
	v_mad_i64_i32 v[68:69], s[26:27], v96, s51, v[120:121]
	v_lshl_add_u64 v[68:69], v[68:69], 0, s[24:25]
	v_lshl_add_u64 v[68:69], v[68:69], 0, s[6:7]
	v_add_u32_e32 v80, 0x80, v152
	v_lshl_add_u64 v[68:69], v[68:69], 0, v[136:137]
	v_ashrrev_i32_e32 v81, 31, v80
	global_store_dwordx4 v[68:69], v[64:67], off
	s_nop 1
	v_lshlrev_b64 v[64:65], 6, v[80:81]
	v_lshl_add_u64 v[76:77], s[74:75], 0, v[64:65]
	global_load_dwordx4 v[64:67], v[76:77], off
	global_load_dwordx4 v[68:71], v[76:77], off offset:16
	global_load_dwordx4 v[72:75], v[76:77], off offset:32
	s_nop 0
	global_load_dwordx4 v[76:79], v[76:77], off offset:48
	s_waitcnt vmcnt(2)
	v_pk_add_f32 v[64:65], v[64:65], v[66:67]
	v_pk_add_f32 v[68:69], v[68:69], v[70:71]
	s_waitcnt vmcnt(0)
	v_pk_add_f32 v[72:73], v[72:73], v[74:75]
	v_pk_add_f32 v[76:77], v[76:77], v[78:79]
	v_pk_add_f32 v[64:65], v[64:65], v[68:69]
	v_pk_add_f32 v[72:73], v[72:73], v[76:77]
	v_mul_f32_e32 v60, v60, v56
	v_mul_f32_e32 v61, v61, v57
	v_mul_f32_e32 v62, v62, v58
	v_mul_f32_e32 v49, v49, v53
	v_pk_add_f32 v[64:65], v[64:65], v[72:73]
	v_mul_f32_e32 v50, v50, v54
	v_mul_f32_e32 v63, v63, v59
	v_mul_f32_e32 v48, v48, v52
	v_mul_f32_e32 v51, v51, v55
	v_add_f32_e32 v64, v64, v65
	v_fmamk_f32 v64, v64, 0x3a800000, v160
	v_rsq_f32_e32 v65, v64
	s_nop 0
	v_mul_f32_e32 v65, 0xbfb8aa3b, v65
	v_mul_f32_e32 v56, v65, v56
	v_mul_f32_e32 v57, v65, v57
	v_mul_f32_e32 v58, v65, v58
	v_mul_f32_e32 v53, v65, v53
	v_mul_f32_e32 v54, v65, v54
	v_mul_f32_e32 v59, v65, v59
	v_mul_f32_e32 v52, v65, v52
	v_mul_f32_e32 v55, v65, v55
	v_exp_f32_e32 v56, v56
	v_exp_f32_e32 v57, v57
	v_exp_f32_e32 v58, v58
	v_exp_f32_e32 v53, v53
	v_exp_f32_e32 v54, v54
	v_exp_f32_e32 v59, v59
	v_exp_f32_e32 v52, v52
	v_exp_f32_e32 v55, v55
	v_fma_f32 v56, v56, v64, v64
	v_fma_f32 v57, v57, v64, v64
	v_fma_f32 v58, v58, v64, v64
	v_fma_f32 v53, v53, v64, v64
	v_fma_f32 v54, v54, v64, v64
	v_fma_f32 v59, v59, v64, v64
	v_fma_f32 v52, v52, v64, v64
	v_fma_f32 v55, v55, v64, v64
	v_rcp_f32_e32 v56, v56
	v_rcp_f32_e32 v57, v57
	v_rcp_f32_e32 v58, v58
	v_rcp_f32_e32 v53, v53
	v_rcp_f32_e32 v54, v54
	v_rcp_f32_e32 v59, v59
	v_rcp_f32_e32 v52, v52
	v_rcp_f32_e32 v55, v55
	v_mul_f32_e32 v60, v60, v56
	v_mul_f32_e32 v61, v61, v57
	v_mul_f32_e32 v62, v62, v58
	v_mul_f32_e32 v49, v49, v53
	v_mul_f32_e32 v50, v50, v54
	v_mul_f32_e32 v63, v63, v59
	v_mul_f32_e32 v48, v48, v52
	v_mul_f32_e32 v51, v51, v55
	v_cvt_pk_bf16_f32 v51, v50, v51
	v_cvt_pk_bf16_f32 v50, v48, v49
	v_cvt_pk_bf16_f32 v48, v60, v61
	v_cvt_pk_bf16_f32 v49, v62, v63
	v_mad_i64_i32 v[52:53], s[26:27], v80, s51, v[120:121]
	v_lshl_add_u64 v[52:53], v[52:53], 0, s[24:25]
	v_lshl_add_u64 v[52:53], v[52:53], 0, s[6:7]
	v_add_u32_e32 v64, 0x90, v152
	v_lshl_add_u64 v[52:53], v[52:53], 0, v[136:137]
	v_ashrrev_i32_e32 v65, 31, v64
	global_store_dwordx4 v[52:53], v[48:51], off
	s_nop 1
	v_lshlrev_b64 v[48:49], 6, v[64:65]
	v_lshl_add_u64 v[60:61], s[74:75], 0, v[48:49]
	global_load_dwordx4 v[48:51], v[60:61], off
	global_load_dwordx4 v[52:55], v[60:61], off offset:16
	global_load_dwordx4 v[56:59], v[60:61], off offset:32
	s_nop 0
	global_load_dwordx4 v[60:63], v[60:61], off offset:48
	s_waitcnt vmcnt(2)
	v_pk_add_f32 v[48:49], v[48:49], v[50:51]
	v_pk_add_f32 v[52:53], v[52:53], v[54:55]
	s_waitcnt vmcnt(0)
	v_pk_add_f32 v[56:57], v[56:57], v[58:59]
	v_pk_add_f32 v[60:61], v[60:61], v[62:63]
	v_pk_add_f32 v[48:49], v[48:49], v[52:53]
	v_pk_add_f32 v[56:57], v[56:57], v[60:61]
	v_mul_f32_e32 v44, v44, v40
	v_mul_f32_e32 v45, v45, v41
	v_mul_f32_e32 v46, v46, v42
	v_mul_f32_e32 v33, v33, v37
	v_pk_add_f32 v[48:49], v[48:49], v[56:57]
	v_mul_f32_e32 v34, v34, v38
	v_mul_f32_e32 v47, v47, v43
	v_mul_f32_e32 v32, v32, v36
	v_mul_f32_e32 v35, v35, v39
	v_add_f32_e32 v48, v48, v49
	v_fmamk_f32 v48, v48, 0x3a800000, v160
	v_rsq_f32_e32 v49, v48
	s_nop 0
	v_mul_f32_e32 v49, 0xbfb8aa3b, v49
	v_mul_f32_e32 v40, v49, v40
	v_mul_f32_e32 v41, v49, v41
	v_mul_f32_e32 v42, v49, v42
	v_mul_f32_e32 v37, v49, v37
	v_mul_f32_e32 v38, v49, v38
	v_mul_f32_e32 v43, v49, v43
	v_mul_f32_e32 v36, v49, v36
	v_mul_f32_e32 v39, v49, v39
	v_exp_f32_e32 v40, v40
	v_exp_f32_e32 v41, v41
	v_exp_f32_e32 v42, v42
	v_exp_f32_e32 v37, v37
	v_exp_f32_e32 v38, v38
	v_exp_f32_e32 v43, v43
	v_exp_f32_e32 v36, v36
	v_exp_f32_e32 v39, v39
	v_fma_f32 v40, v40, v48, v48
	v_fma_f32 v41, v41, v48, v48
	v_fma_f32 v42, v42, v48, v48
	v_fma_f32 v37, v37, v48, v48
	v_fma_f32 v38, v38, v48, v48
	v_fma_f32 v43, v43, v48, v48
	v_fma_f32 v36, v36, v48, v48
	v_fma_f32 v39, v39, v48, v48
	v_rcp_f32_e32 v40, v40
	v_rcp_f32_e32 v41, v41
	v_rcp_f32_e32 v42, v42
	v_rcp_f32_e32 v37, v37
	v_rcp_f32_e32 v38, v38
	v_rcp_f32_e32 v43, v43
	v_rcp_f32_e32 v36, v36
	v_rcp_f32_e32 v39, v39
	v_mul_f32_e32 v44, v44, v40
	v_mul_f32_e32 v45, v45, v41
	v_mul_f32_e32 v46, v46, v42
	v_mul_f32_e32 v33, v33, v37
	v_mul_f32_e32 v34, v34, v38
	v_mul_f32_e32 v47, v47, v43
	v_mul_f32_e32 v32, v32, v36
	v_mul_f32_e32 v35, v35, v39
	v_cvt_pk_bf16_f32 v35, v34, v35
	v_cvt_pk_bf16_f32 v34, v32, v33
	v_cvt_pk_bf16_f32 v32, v44, v45
	v_cvt_pk_bf16_f32 v33, v46, v47
	v_mad_i64_i32 v[36:37], s[26:27], v64, s51, v[120:121]
	v_lshl_add_u64 v[36:37], v[36:37], 0, s[24:25]
	v_lshl_add_u64 v[36:37], v[36:37], 0, s[6:7]
	v_add_u32_e32 v48, 0xa0, v152
	v_lshl_add_u64 v[36:37], v[36:37], 0, v[136:137]
	v_ashrrev_i32_e32 v49, 31, v48
	global_store_dwordx4 v[36:37], v[32:35], off
	s_nop 1
	v_lshlrev_b64 v[32:33], 6, v[48:49]
	v_lshl_add_u64 v[44:45], s[74:75], 0, v[32:33]
	global_load_dwordx4 v[32:35], v[44:45], off
	global_load_dwordx4 v[36:39], v[44:45], off offset:16
	global_load_dwordx4 v[40:43], v[44:45], off offset:32
	s_nop 0
	global_load_dwordx4 v[44:47], v[44:45], off offset:48
	s_waitcnt vmcnt(2)
	v_pk_add_f32 v[32:33], v[32:33], v[34:35]
	v_pk_add_f32 v[36:37], v[36:37], v[38:39]
	s_waitcnt vmcnt(0)
	v_pk_add_f32 v[40:41], v[40:41], v[42:43]
	v_pk_add_f32 v[44:45], v[44:45], v[46:47]
	v_pk_add_f32 v[32:33], v[32:33], v[36:37]
	v_pk_add_f32 v[40:41], v[40:41], v[44:45]
	v_mul_f32_e32 v28, v28, v24
	v_mul_f32_e32 v29, v29, v25
	v_mul_f32_e32 v30, v30, v26
	v_mul_f32_e32 v17, v17, v21
	v_pk_add_f32 v[32:33], v[32:33], v[40:41]
	v_mul_f32_e32 v18, v18, v22
	v_mul_f32_e32 v31, v31, v27
	v_mul_f32_e32 v16, v16, v20
	v_mul_f32_e32 v19, v19, v23
	v_add_f32_e32 v32, v32, v33
	v_fmamk_f32 v32, v32, 0x3a800000, v160
	v_rsq_f32_e32 v33, v32
	s_nop 0
	v_mul_f32_e32 v33, 0xbfb8aa3b, v33
	v_mul_f32_e32 v24, v33, v24
	v_mul_f32_e32 v25, v33, v25
	v_mul_f32_e32 v26, v33, v26
	v_mul_f32_e32 v21, v33, v21
	v_mul_f32_e32 v22, v33, v22
	v_mul_f32_e32 v27, v33, v27
	v_mul_f32_e32 v20, v33, v20
	v_mul_f32_e32 v23, v33, v23
	v_exp_f32_e32 v24, v24
	v_exp_f32_e32 v25, v25
	v_exp_f32_e32 v26, v26
	v_exp_f32_e32 v21, v21
	v_exp_f32_e32 v22, v22
	v_exp_f32_e32 v27, v27
	v_exp_f32_e32 v20, v20
	v_exp_f32_e32 v23, v23
	v_fma_f32 v24, v24, v32, v32
	v_fma_f32 v25, v25, v32, v32
	v_fma_f32 v26, v26, v32, v32
	v_fma_f32 v21, v21, v32, v32
	v_fma_f32 v22, v22, v32, v32
	v_fma_f32 v27, v27, v32, v32
	v_fma_f32 v20, v20, v32, v32
	v_fma_f32 v23, v23, v32, v32
	v_rcp_f32_e32 v24, v24
	v_rcp_f32_e32 v25, v25
	v_rcp_f32_e32 v26, v26
	v_rcp_f32_e32 v21, v21
	v_rcp_f32_e32 v22, v22
	v_rcp_f32_e32 v27, v27
	v_rcp_f32_e32 v20, v20
	v_rcp_f32_e32 v23, v23
	v_mul_f32_e32 v28, v28, v24
	v_mul_f32_e32 v29, v29, v25
	v_mul_f32_e32 v30, v30, v26
	v_mul_f32_e32 v17, v17, v21
	v_mul_f32_e32 v18, v18, v22
	v_mul_f32_e32 v31, v31, v27
	v_mul_f32_e32 v16, v16, v20
	v_mul_f32_e32 v19, v19, v23
	v_cvt_pk_bf16_f32 v19, v18, v19
	v_cvt_pk_bf16_f32 v18, v16, v17
	v_cvt_pk_bf16_f32 v16, v28, v29
	v_cvt_pk_bf16_f32 v17, v30, v31
	v_mad_i64_i32 v[20:21], s[26:27], v48, s51, v[120:121]
	v_lshl_add_u64 v[20:21], v[20:21], 0, s[24:25]
	v_lshl_add_u64 v[20:21], v[20:21], 0, s[6:7]
	v_add_u32_e32 v32, 0xb0, v152
	v_lshl_add_u64 v[20:21], v[20:21], 0, v[136:137]
	v_ashrrev_i32_e32 v33, 31, v32
	global_store_dwordx4 v[20:21], v[16:19], off
	s_nop 1
	v_lshlrev_b64 v[16:17], 6, v[32:33]
	v_lshl_add_u64 v[28:29], s[74:75], 0, v[16:17]
	global_load_dwordx4 v[16:19], v[28:29], off
	global_load_dwordx4 v[20:23], v[28:29], off offset:16
	global_load_dwordx4 v[24:27], v[28:29], off offset:32
	s_nop 0
	global_load_dwordx4 v[28:31], v[28:29], off offset:48
	s_waitcnt vmcnt(2)
	v_pk_add_f32 v[16:17], v[16:17], v[18:19]
	v_pk_add_f32 v[20:21], v[20:21], v[22:23]
	s_waitcnt vmcnt(0)
	v_pk_add_f32 v[24:25], v[24:25], v[26:27]
	v_pk_add_f32 v[28:29], v[28:29], v[30:31]
	v_pk_add_f32 v[16:17], v[16:17], v[20:21]
	v_pk_add_f32 v[24:25], v[24:25], v[28:29]
	v_mul_f32_e32 v12, v12, v8
	v_mul_f32_e32 v13, v13, v9
	v_mul_f32_e32 v14, v14, v10
	v_mul_f32_e32 v1, v1, v5
	v_pk_add_f32 v[16:17], v[16:17], v[24:25]
	v_mul_f32_e32 v2, v2, v6
	v_mul_f32_e32 v15, v15, v11
	v_mul_f32_e32 v0, v0, v4
	v_mul_f32_e32 v3, v3, v7
	v_add_f32_e32 v16, v16, v17
	v_fmamk_f32 v16, v16, 0x3a800000, v160
	v_rsq_f32_e32 v17, v16
	s_nop 0
	v_mul_f32_e32 v17, 0xbfb8aa3b, v17
	v_mul_f32_e32 v8, v17, v8
	v_mul_f32_e32 v9, v17, v9
	v_mul_f32_e32 v10, v17, v10
	v_mul_f32_e32 v5, v17, v5
	v_mul_f32_e32 v6, v17, v6
	v_mul_f32_e32 v11, v17, v11
	v_mul_f32_e32 v4, v17, v4
	v_mul_f32_e32 v7, v17, v7
	v_exp_f32_e32 v8, v8
	v_exp_f32_e32 v9, v9
	v_exp_f32_e32 v10, v10
	v_exp_f32_e32 v5, v5
	v_exp_f32_e32 v6, v6
	v_exp_f32_e32 v11, v11
	v_exp_f32_e32 v4, v4
	v_exp_f32_e32 v7, v7
	v_fma_f32 v8, v8, v16, v16
	v_fma_f32 v9, v9, v16, v16
	v_fma_f32 v10, v10, v16, v16
	v_fma_f32 v5, v5, v16, v16
	v_fma_f32 v6, v6, v16, v16
	v_fma_f32 v11, v11, v16, v16
	v_fma_f32 v4, v4, v16, v16
	v_fma_f32 v7, v7, v16, v16
	v_rcp_f32_e32 v8, v8
	v_rcp_f32_e32 v9, v9
	v_rcp_f32_e32 v10, v10
	v_rcp_f32_e32 v5, v5
	v_rcp_f32_e32 v6, v6
	v_rcp_f32_e32 v11, v11
	v_rcp_f32_e32 v4, v4
	v_rcp_f32_e32 v7, v7
	v_mul_f32_e32 v12, v12, v8
	v_mul_f32_e32 v13, v13, v9
	v_mul_f32_e32 v14, v14, v10
	v_mul_f32_e32 v1, v1, v5
	v_mul_f32_e32 v2, v2, v6
	v_mul_f32_e32 v15, v15, v11
	v_mul_f32_e32 v0, v0, v4
	v_mul_f32_e32 v3, v3, v7
	v_cvt_pk_bf16_f32 v3, v2, v3
	v_cvt_pk_bf16_f32 v2, v0, v1
	v_cvt_pk_bf16_f32 v0, v12, v13
	v_cvt_pk_bf16_f32 v1, v14, v15
	v_mad_i64_i32 v[4:5], s[26:27], v32, s51, v[120:121]
	v_lshl_add_u64 v[4:5], v[4:5], 0, s[24:25]
	v_lshl_add_u64 v[4:5], v[4:5], 0, s[6:7]
	v_lshl_add_u64 v[4:5], v[4:5], 0, v[136:137]
	global_store_dwordx4 v[4:5], v[0:3], off
	s_nop 1
	s_andn2_b64 vcc, exec, s[4:5]
	s_mov_b64 s[4:5], -1
	s_cbranch_vccnz .LBB0_157
	s_branch .LBB0_191

.LBB0_981:
	v_ashrrev_i32_e32 v153, 31, v152
	v_lshlrev_b64 v[154:155], 6, v[152:153]
	v_lshl_add_u64 v[170:171], s[74:75], 0, v[154:155]
	s_waitcnt lgkmcnt(0)
	global_load_dwordx4 v[154:157], v[170:171], off
	global_load_dwordx4 v[162:165], v[170:171], off offset:16
	global_load_dwordx4 v[166:169], v[170:171], off offset:32
	s_nop 0
	global_load_dwordx4 v[170:173], v[170:171], off offset:48
	s_lshl_b32 s26, s26, 7
	v_mov_b32_e32 v174, v124
	v_mov_b32_e32 v124, v126
	v_mov_b32_e32 v126, v120
	v_mov_b32_e32 v175, v116
	v_mov_b32_e32 v116, v125
	v_mov_b32_e32 v125, v118
	v_mov_b32_e32 v118, v127
	v_mov_b32_e32 v127, v112
	v_mov_b32_e32 v112, v121
	v_mov_b64_e32 v[120:121], s[72:73]
	s_ashr_i32 s27, s26, 31
	v_mov_b32_e32 v176, v122
	v_mov_b32_e32 v177, v114
	v_mov_b32_e32 v114, v123
	v_mad_i64_i32 v[122:123], s[28:29], v152, s53, v[120:121]
	s_lshl_b64 s[26:27], s[26:27], 1
	v_lshl_add_u64 v[122:123], v[122:123], 0, s[26:27]
	v_lshl_add_u64 v[122:123], v[122:123], 0, s[8:9]
	s_waitcnt vmcnt(2)
	v_pk_add_f32 v[154:155], v[154:155], v[156:157]
	v_pk_add_f32 v[162:163], v[162:163], v[164:165]
	s_waitcnt vmcnt(0)
	v_pk_add_f32 v[166:167], v[166:167], v[168:169]
	v_pk_add_f32 v[170:171], v[170:171], v[172:173]
	v_pk_add_f32 v[154:155], v[154:155], v[162:163]
	v_pk_add_f32 v[166:167], v[166:167], v[170:171]
	v_mul_f32_e32 v116, v116, v117
	v_mul_f32_e32 v124, v124, v125
	v_mul_f32_e32 v118, v118, v119
	v_mul_f32_e32 v126, v126, v127
	v_pk_add_f32 v[154:155], v[154:155], v[166:167]
	v_mul_f32_e32 v174, v174, v175
	v_mul_f32_e32 v112, v112, v113
	v_mul_f32_e32 v176, v176, v177
	v_mul_f32_e32 v114, v114, v115
	v_add_f32_e32 v154, v154, v155
	v_fmamk_f32 v154, v154, 0x3a800000, v160
	v_rsq_f32_e32 v155, v154
	s_nop 0
	v_mul_f32_e32 v155, 0xbfb8aa3b, v155
	v_mul_f32_e32 v117, v155, v117
	v_mul_f32_e32 v125, v155, v125
	v_mul_f32_e32 v119, v155, v119
	v_mul_f32_e32 v127, v155, v127
	v_mul_f32_e32 v175, v155, v175
	v_mul_f32_e32 v113, v155, v113
	v_mul_f32_e32 v177, v155, v177
	v_mul_f32_e32 v115, v155, v115
	v_exp_f32_e32 v117, v117
	v_exp_f32_e32 v125, v125
	v_exp_f32_e32 v119, v119
	v_exp_f32_e32 v127, v127
	v_exp_f32_e32 v175, v175
	v_exp_f32_e32 v113, v113
	v_exp_f32_e32 v177, v177
	v_exp_f32_e32 v115, v115
	v_fma_f32 v117, v117, v154, v154
	v_fma_f32 v125, v125, v154, v154
	v_fma_f32 v119, v119, v154, v154
	v_fma_f32 v127, v127, v154, v154
	v_fma_f32 v175, v175, v154, v154
	v_fma_f32 v113, v113, v154, v154
	v_fma_f32 v177, v177, v154, v154
	v_fma_f32 v115, v115, v154, v154
	v_rcp_f32_e32 v117, v117
	v_rcp_f32_e32 v125, v125
	v_rcp_f32_e32 v119, v119
	v_rcp_f32_e32 v127, v127
	v_rcp_f32_e32 v175, v175
	v_rcp_f32_e32 v113, v113
	v_rcp_f32_e32 v177, v177
	v_rcp_f32_e32 v115, v115
	v_mul_f32_e32 v116, v116, v117
	v_mul_f32_e32 v124, v124, v125
	v_mul_f32_e32 v118, v118, v119
	v_mul_f32_e32 v126, v126, v127
	v_mul_f32_e32 v174, v174, v175
	v_mul_f32_e32 v112, v112, v113
	v_mul_f32_e32 v176, v176, v177
	v_mul_f32_e32 v114, v114, v115
	v_cvt_pk_bf16_f32 v113, v124, v118
	v_cvt_pk_bf16_f32 v115, v176, v114
	v_cvt_pk_bf16_f32 v114, v126, v112
	v_cvt_pk_bf16_f32 v112, v174, v116
	v_or_b32_e32 v126, 16, v152
	v_lshl_add_u64 v[116:117], v[122:123], 0, v[136:137]
	v_ashrrev_i32_e32 v127, 31, v126
	global_store_dwordx4 v[116:117], v[112:115], off
	s_nop 1
	v_lshlrev_b64 v[112:113], 6, v[126:127]
	v_lshl_add_u64 v[154:155], s[74:75], 0, v[112:113]
	global_load_dwordx4 v[112:115], v[154:155], off
	global_load_dwordx4 v[116:119], v[154:155], off offset:16
	global_load_dwordx4 v[122:125], v[154:155], off offset:32
	s_nop 0
	global_load_dwordx4 v[154:157], v[154:155], off offset:48
	s_waitcnt vmcnt(2)
	v_pk_add_f32 v[112:113], v[112:113], v[114:115]
	v_pk_add_f32 v[116:117], v[116:117], v[118:119]
	s_waitcnt vmcnt(0)
	v_pk_add_f32 v[122:123], v[122:123], v[124:125]
	v_pk_add_f32 v[154:155], v[154:155], v[156:157]
	v_pk_add_f32 v[112:113], v[112:113], v[116:117]
	v_pk_add_f32 v[122:123], v[122:123], v[154:155]
	v_mul_f32_e32 v109, v109, v101
	v_mul_f32_e32 v110, v110, v102
	v_mul_f32_e32 v108, v108, v100
	v_mul_f32_e32 v111, v111, v103
	v_pk_add_f32 v[112:113], v[112:113], v[122:123]
	v_mul_f32_e32 v104, v104, v96
	v_mul_f32_e32 v105, v105, v97
	v_mul_f32_e32 v106, v106, v98
	v_mul_f32_e32 v107, v107, v99
	v_add_f32_e32 v112, v112, v113
	v_fmamk_f32 v112, v112, 0x3a800000, v160
	v_rsq_f32_e32 v113, v112
	s_nop 0
	v_mul_f32_e32 v113, 0xbfb8aa3b, v113
	v_mul_f32_e32 v101, v113, v101
	v_mul_f32_e32 v102, v113, v102
	v_mul_f32_e32 v100, v113, v100
	v_mul_f32_e32 v103, v113, v103
	v_mul_f32_e32 v96, v113, v96
	v_mul_f32_e32 v97, v113, v97
	v_mul_f32_e32 v98, v113, v98
	v_mul_f32_e32 v99, v113, v99
	v_exp_f32_e32 v101, v101
	v_exp_f32_e32 v102, v102
	v_exp_f32_e32 v100, v100
	v_exp_f32_e32 v103, v103
	v_exp_f32_e32 v96, v96
	v_exp_f32_e32 v97, v97
	v_exp_f32_e32 v98, v98
	v_exp_f32_e32 v99, v99
	v_fma_f32 v101, v101, v112, v112
	v_fma_f32 v102, v102, v112, v112
	v_fma_f32 v100, v100, v112, v112
	v_fma_f32 v103, v103, v112, v112
	v_fma_f32 v96, v96, v112, v112
	v_fma_f32 v97, v97, v112, v112
	v_fma_f32 v98, v98, v112, v112
	v_fma_f32 v99, v99, v112, v112
	v_rcp_f32_e32 v101, v101
	v_rcp_f32_e32 v102, v102
	v_rcp_f32_e32 v100, v100
	v_rcp_f32_e32 v103, v103
	v_rcp_f32_e32 v96, v96
	v_rcp_f32_e32 v97, v97
	v_rcp_f32_e32 v98, v98
	v_rcp_f32_e32 v99, v99
	v_mul_f32_e32 v109, v109, v101
	v_mul_f32_e32 v110, v110, v102
	v_mul_f32_e32 v108, v108, v100
	v_mul_f32_e32 v111, v111, v103
	v_mul_f32_e32 v104, v104, v96
	v_mul_f32_e32 v105, v105, v97
	v_mul_f32_e32 v106, v106, v98
	v_mul_f32_e32 v107, v107, v99
	v_cvt_pk_bf16_f32 v96, v108, v109
	v_cvt_pk_bf16_f32 v97, v110, v111
	v_cvt_pk_bf16_f32 v98, v104, v105
	v_cvt_pk_bf16_f32 v99, v106, v107
	v_mad_i64_i32 v[112:113], s[28:29], v126, s53, v[120:121]
	v_lshl_add_u64 v[112:113], v[112:113], 0, s[26:27]
	v_lshl_add_u64 v[100:101], v[112:113], 0, s[8:9]
	v_or_b32_e32 v112, 32, v152
	v_lshl_add_u64 v[100:101], v[100:101], 0, v[136:137]
	v_ashrrev_i32_e32 v113, 31, v112
	global_store_dwordx4 v[100:101], v[96:99], off
	s_nop 1
	v_lshlrev_b64 v[96:97], 6, v[112:113]
	v_lshl_add_u64 v[108:109], s[74:75], 0, v[96:97]
	global_load_dwordx4 v[96:99], v[108:109], off
	global_load_dwordx4 v[100:103], v[108:109], off offset:16
	global_load_dwordx4 v[104:107], v[108:109], off offset:32
	s_nop 0
	global_load_dwordx4 v[108:111], v[108:109], off offset:48
	s_waitcnt vmcnt(2)
	v_pk_add_f32 v[96:97], v[96:97], v[98:99]
	v_pk_add_f32 v[100:101], v[100:101], v[102:103]
	s_waitcnt vmcnt(0)
	v_pk_add_f32 v[104:105], v[104:105], v[106:107]
	v_pk_add_f32 v[108:109], v[108:109], v[110:111]
	v_pk_add_f32 v[96:97], v[96:97], v[100:101]
	v_pk_add_f32 v[104:105], v[104:105], v[108:109]
	v_mul_f32_e32 v92, v92, v88
	v_mul_f32_e32 v93, v93, v89
	v_mul_f32_e32 v94, v94, v90
	v_mul_f32_e32 v95, v95, v91
	v_pk_add_f32 v[96:97], v[96:97], v[104:105]
	v_mul_f32_e32 v80, v80, v84
	v_mul_f32_e32 v81, v81, v85
	v_mul_f32_e32 v82, v82, v86
	v_mul_f32_e32 v83, v83, v87
	v_add_f32_e32 v96, v96, v97
	v_fmamk_f32 v96, v96, 0x3a800000, v160
	v_rsq_f32_e32 v97, v96
	s_nop 0
	v_mul_f32_e32 v97, 0xbfb8aa3b, v97
	v_mul_f32_e32 v88, v97, v88
	v_mul_f32_e32 v89, v97, v89
	v_mul_f32_e32 v90, v97, v90
	v_mul_f32_e32 v91, v97, v91
	v_mul_f32_e32 v84, v97, v84
	v_mul_f32_e32 v85, v97, v85
	v_mul_f32_e32 v86, v97, v86
	v_mul_f32_e32 v87, v97, v87
	v_exp_f32_e32 v88, v88
	v_exp_f32_e32 v89, v89
	v_exp_f32_e32 v90, v90
	v_exp_f32_e32 v91, v91
	v_exp_f32_e32 v84, v84
	v_exp_f32_e32 v85, v85
	v_exp_f32_e32 v86, v86
	v_exp_f32_e32 v87, v87
	v_fma_f32 v88, v88, v96, v96
	v_fma_f32 v89, v89, v96, v96
	v_fma_f32 v90, v90, v96, v96
	v_fma_f32 v91, v91, v96, v96
	v_fma_f32 v84, v84, v96, v96
	v_fma_f32 v85, v85, v96, v96
	v_fma_f32 v86, v86, v96, v96
	v_fma_f32 v87, v87, v96, v96
	v_rcp_f32_e32 v88, v88
	v_rcp_f32_e32 v89, v89
	v_rcp_f32_e32 v90, v90
	v_rcp_f32_e32 v91, v91
	v_rcp_f32_e32 v84, v84
	v_rcp_f32_e32 v85, v85
	v_rcp_f32_e32 v86, v86
	v_rcp_f32_e32 v87, v87
	v_mul_f32_e32 v92, v92, v88
	v_mul_f32_e32 v93, v93, v89
	v_mul_f32_e32 v94, v94, v90
	v_mul_f32_e32 v95, v95, v91
	v_mul_f32_e32 v80, v80, v84
	v_mul_f32_e32 v81, v81, v85
	v_mul_f32_e32 v82, v82, v86
	v_mul_f32_e32 v83, v83, v87
	v_cvt_pk_bf16_f32 v83, v82, v83
	v_cvt_pk_bf16_f32 v82, v80, v81
	v_cvt_pk_bf16_f32 v80, v92, v93
	v_cvt_pk_bf16_f32 v81, v94, v95
	v_mad_i64_i32 v[96:97], s[28:29], v112, s53, v[120:121]
	v_lshl_add_u64 v[84:85], v[96:97], 0, s[26:27]
	v_lshl_add_u64 v[84:85], v[84:85], 0, s[8:9]
	v_or_b32_e32 v96, 48, v152
	v_lshl_add_u64 v[84:85], v[84:85], 0, v[136:137]
	v_ashrrev_i32_e32 v97, 31, v96
	global_store_dwordx4 v[84:85], v[80:83], off
	s_nop 1
	v_lshlrev_b64 v[80:81], 6, v[96:97]
	v_lshl_add_u64 v[92:93], s[74:75], 0, v[80:81]
	global_load_dwordx4 v[80:83], v[92:93], off
	global_load_dwordx4 v[84:87], v[92:93], off offset:16
	global_load_dwordx4 v[88:91], v[92:93], off offset:32
	s_nop 0
	global_load_dwordx4 v[92:95], v[92:93], off offset:48
	s_waitcnt vmcnt(2)
	v_pk_add_f32 v[80:81], v[80:81], v[82:83]
	v_pk_add_f32 v[84:85], v[84:85], v[86:87]
	s_waitcnt vmcnt(0)
	v_pk_add_f32 v[88:89], v[88:89], v[90:91]
	v_pk_add_f32 v[92:93], v[92:93], v[94:95]
	v_pk_add_f32 v[80:81], v[80:81], v[84:85]
	v_pk_add_f32 v[88:89], v[88:89], v[92:93]
	v_mul_f32_e32 v76, v76, v72
	v_mul_f32_e32 v77, v77, v73
	v_mul_f32_e32 v78, v78, v74
	v_mul_f32_e32 v65, v65, v69
	v_pk_add_f32 v[80:81], v[80:81], v[88:89]
	v_mul_f32_e32 v66, v66, v70
	v_mul_f32_e32 v79, v79, v75
	v_mul_f32_e32 v64, v64, v68
	v_mul_f32_e32 v67, v67, v71
	v_add_f32_e32 v80, v80, v81
	v_fmamk_f32 v80, v80, 0x3a800000, v160
	v_rsq_f32_e32 v81, v80
	s_nop 0
	v_mul_f32_e32 v81, 0xbfb8aa3b, v81
	v_mul_f32_e32 v72, v81, v72
	v_mul_f32_e32 v73, v81, v73
	v_mul_f32_e32 v74, v81, v74
	v_mul_f32_e32 v69, v81, v69
	v_mul_f32_e32 v70, v81, v70
	v_mul_f32_e32 v75, v81, v75
	v_mul_f32_e32 v68, v81, v68
	v_mul_f32_e32 v71, v81, v71
	v_exp_f32_e32 v72, v72
	v_exp_f32_e32 v73, v73
	v_exp_f32_e32 v74, v74
	v_exp_f32_e32 v69, v69
	v_exp_f32_e32 v70, v70
	v_exp_f32_e32 v75, v75
	v_exp_f32_e32 v68, v68
	v_exp_f32_e32 v71, v71
	v_fma_f32 v72, v72, v80, v80
	v_fma_f32 v73, v73, v80, v80
	v_fma_f32 v74, v74, v80, v80
	v_fma_f32 v69, v69, v80, v80
	v_fma_f32 v70, v70, v80, v80
	v_fma_f32 v75, v75, v80, v80
	v_fma_f32 v68, v68, v80, v80
	v_fma_f32 v71, v71, v80, v80
	v_rcp_f32_e32 v72, v72
	v_rcp_f32_e32 v73, v73
	v_rcp_f32_e32 v74, v74
	v_rcp_f32_e32 v69, v69
	v_rcp_f32_e32 v70, v70
	v_rcp_f32_e32 v75, v75
	v_rcp_f32_e32 v68, v68
	v_rcp_f32_e32 v71, v71
	v_mul_f32_e32 v76, v76, v72
	v_mul_f32_e32 v77, v77, v73
	v_mul_f32_e32 v78, v78, v74
	v_mul_f32_e32 v65, v65, v69
	v_mul_f32_e32 v66, v66, v70
	v_mul_f32_e32 v79, v79, v75
	v_mul_f32_e32 v64, v64, v68
	v_mul_f32_e32 v67, v67, v71
	v_cvt_pk_bf16_f32 v67, v66, v67
	v_cvt_pk_bf16_f32 v66, v64, v65
	v_cvt_pk_bf16_f32 v64, v76, v77
	v_cvt_pk_bf16_f32 v65, v78, v79
	v_mad_i64_i32 v[68:69], s[28:29], v96, s53, v[120:121]
	v_lshl_add_u64 v[68:69], v[68:69], 0, s[26:27]
	v_lshl_add_u64 v[68:69], v[68:69], 0, s[8:9]
	v_add_u32_e32 v80, 0x80, v152
	v_lshl_add_u64 v[68:69], v[68:69], 0, v[136:137]
	v_ashrrev_i32_e32 v81, 31, v80
	global_store_dwordx4 v[68:69], v[64:67], off
	s_nop 1
	v_lshlrev_b64 v[64:65], 6, v[80:81]
	v_lshl_add_u64 v[76:77], s[74:75], 0, v[64:65]
	global_load_dwordx4 v[64:67], v[76:77], off
	global_load_dwordx4 v[68:71], v[76:77], off offset:16
	global_load_dwordx4 v[72:75], v[76:77], off offset:32
	s_nop 0
	global_load_dwordx4 v[76:79], v[76:77], off offset:48
	s_waitcnt vmcnt(2)
	v_pk_add_f32 v[64:65], v[64:65], v[66:67]
	v_pk_add_f32 v[68:69], v[68:69], v[70:71]
	s_waitcnt vmcnt(0)
	v_pk_add_f32 v[72:73], v[72:73], v[74:75]
	v_pk_add_f32 v[76:77], v[76:77], v[78:79]
	v_pk_add_f32 v[64:65], v[64:65], v[68:69]
	v_pk_add_f32 v[72:73], v[72:73], v[76:77]
	v_mul_f32_e32 v60, v60, v56
	v_mul_f32_e32 v61, v61, v57
	v_mul_f32_e32 v62, v62, v58
	v_mul_f32_e32 v49, v49, v53
	v_pk_add_f32 v[64:65], v[64:65], v[72:73]
	v_mul_f32_e32 v50, v50, v54
	v_mul_f32_e32 v63, v63, v59
	v_mul_f32_e32 v48, v48, v52
	v_mul_f32_e32 v51, v51, v55
	v_add_f32_e32 v64, v64, v65
	v_fmamk_f32 v64, v64, 0x3a800000, v160
	v_rsq_f32_e32 v65, v64
	s_nop 0
	v_mul_f32_e32 v65, 0xbfb8aa3b, v65
	v_mul_f32_e32 v56, v65, v56
	v_mul_f32_e32 v57, v65, v57
	v_mul_f32_e32 v58, v65, v58
	v_mul_f32_e32 v53, v65, v53
	v_mul_f32_e32 v54, v65, v54
	v_mul_f32_e32 v59, v65, v59
	v_mul_f32_e32 v52, v65, v52
	v_mul_f32_e32 v55, v65, v55
	v_exp_f32_e32 v56, v56
	v_exp_f32_e32 v57, v57
	v_exp_f32_e32 v58, v58
	v_exp_f32_e32 v53, v53
	v_exp_f32_e32 v54, v54
	v_exp_f32_e32 v59, v59
	v_exp_f32_e32 v52, v52
	v_exp_f32_e32 v55, v55
	v_fma_f32 v56, v56, v64, v64
	v_fma_f32 v57, v57, v64, v64
	v_fma_f32 v58, v58, v64, v64
	v_fma_f32 v53, v53, v64, v64
	v_fma_f32 v54, v54, v64, v64
	v_fma_f32 v59, v59, v64, v64
	v_fma_f32 v52, v52, v64, v64
	v_fma_f32 v55, v55, v64, v64
	v_rcp_f32_e32 v56, v56
	v_rcp_f32_e32 v57, v57
	v_rcp_f32_e32 v58, v58
	v_rcp_f32_e32 v53, v53
	v_rcp_f32_e32 v54, v54
	v_rcp_f32_e32 v59, v59
	v_rcp_f32_e32 v52, v52
	v_rcp_f32_e32 v55, v55
	v_mul_f32_e32 v60, v60, v56
	v_mul_f32_e32 v61, v61, v57
	v_mul_f32_e32 v62, v62, v58
	v_mul_f32_e32 v49, v49, v53
	v_mul_f32_e32 v50, v50, v54
	v_mul_f32_e32 v63, v63, v59
	v_mul_f32_e32 v48, v48, v52
	v_mul_f32_e32 v51, v51, v55
	v_cvt_pk_bf16_f32 v51, v50, v51
	v_cvt_pk_bf16_f32 v50, v48, v49
	v_cvt_pk_bf16_f32 v48, v60, v61
	v_cvt_pk_bf16_f32 v49, v62, v63
	v_mad_i64_i32 v[52:53], s[28:29], v80, s53, v[120:121]
	v_lshl_add_u64 v[52:53], v[52:53], 0, s[26:27]
	v_lshl_add_u64 v[52:53], v[52:53], 0, s[8:9]
	v_add_u32_e32 v64, 0x90, v152
	v_lshl_add_u64 v[52:53], v[52:53], 0, v[136:137]
	v_ashrrev_i32_e32 v65, 31, v64
	global_store_dwordx4 v[52:53], v[48:51], off
	s_nop 1
	v_lshlrev_b64 v[48:49], 6, v[64:65]
	v_lshl_add_u64 v[60:61], s[74:75], 0, v[48:49]
	global_load_dwordx4 v[48:51], v[60:61], off
	global_load_dwordx4 v[52:55], v[60:61], off offset:16
	global_load_dwordx4 v[56:59], v[60:61], off offset:32
	s_nop 0
	global_load_dwordx4 v[60:63], v[60:61], off offset:48
	s_waitcnt vmcnt(2)
	v_pk_add_f32 v[48:49], v[48:49], v[50:51]
	v_pk_add_f32 v[52:53], v[52:53], v[54:55]
	s_waitcnt vmcnt(0)
	v_pk_add_f32 v[56:57], v[56:57], v[58:59]
	v_pk_add_f32 v[60:61], v[60:61], v[62:63]
	v_pk_add_f32 v[48:49], v[48:49], v[52:53]
	v_pk_add_f32 v[56:57], v[56:57], v[60:61]
	v_mul_f32_e32 v44, v44, v40
	v_mul_f32_e32 v45, v45, v41
	v_mul_f32_e32 v46, v46, v42
	v_mul_f32_e32 v33, v33, v37
	v_pk_add_f32 v[48:49], v[48:49], v[56:57]
	v_mul_f32_e32 v34, v34, v38
	v_mul_f32_e32 v47, v47, v43
	v_mul_f32_e32 v32, v32, v36
	v_mul_f32_e32 v35, v35, v39
	v_add_f32_e32 v48, v48, v49
	v_fmamk_f32 v48, v48, 0x3a800000, v160
	v_rsq_f32_e32 v49, v48
	s_nop 0
	v_mul_f32_e32 v49, 0xbfb8aa3b, v49
	v_mul_f32_e32 v40, v49, v40
	v_mul_f32_e32 v41, v49, v41
	v_mul_f32_e32 v42, v49, v42
	v_mul_f32_e32 v37, v49, v37
	v_mul_f32_e32 v38, v49, v38
	v_mul_f32_e32 v43, v49, v43
	v_mul_f32_e32 v36, v49, v36
	v_mul_f32_e32 v39, v49, v39
	v_exp_f32_e32 v40, v40
	v_exp_f32_e32 v41, v41
	v_exp_f32_e32 v42, v42
	v_exp_f32_e32 v37, v37
	v_exp_f32_e32 v38, v38
	v_exp_f32_e32 v43, v43
	v_exp_f32_e32 v36, v36
	v_exp_f32_e32 v39, v39
	v_fma_f32 v40, v40, v48, v48
	v_fma_f32 v41, v41, v48, v48
	v_fma_f32 v42, v42, v48, v48
	v_fma_f32 v37, v37, v48, v48
	v_fma_f32 v38, v38, v48, v48
	v_fma_f32 v43, v43, v48, v48
	v_fma_f32 v36, v36, v48, v48
	v_fma_f32 v39, v39, v48, v48
	v_rcp_f32_e32 v40, v40
	v_rcp_f32_e32 v41, v41
	v_rcp_f32_e32 v42, v42
	v_rcp_f32_e32 v37, v37
	v_rcp_f32_e32 v38, v38
	v_rcp_f32_e32 v43, v43
	v_rcp_f32_e32 v36, v36
	v_rcp_f32_e32 v39, v39
	v_mul_f32_e32 v44, v44, v40
	v_mul_f32_e32 v45, v45, v41
	v_mul_f32_e32 v46, v46, v42
	v_mul_f32_e32 v33, v33, v37
	v_mul_f32_e32 v34, v34, v38
	v_mul_f32_e32 v47, v47, v43
	v_mul_f32_e32 v32, v32, v36
	v_mul_f32_e32 v35, v35, v39
	v_cvt_pk_bf16_f32 v35, v34, v35
	v_cvt_pk_bf16_f32 v34, v32, v33
	v_cvt_pk_bf16_f32 v32, v44, v45
	v_cvt_pk_bf16_f32 v33, v46, v47
	v_mad_i64_i32 v[36:37], s[28:29], v64, s53, v[120:121]
	v_lshl_add_u64 v[36:37], v[36:37], 0, s[26:27]
	v_lshl_add_u64 v[36:37], v[36:37], 0, s[8:9]
	v_add_u32_e32 v48, 0xa0, v152
	v_lshl_add_u64 v[36:37], v[36:37], 0, v[136:137]
	v_ashrrev_i32_e32 v49, 31, v48
	global_store_dwordx4 v[36:37], v[32:35], off
	s_nop 1
	v_lshlrev_b64 v[32:33], 6, v[48:49]
	v_lshl_add_u64 v[44:45], s[74:75], 0, v[32:33]
	global_load_dwordx4 v[32:35], v[44:45], off
	global_load_dwordx4 v[36:39], v[44:45], off offset:16
	global_load_dwordx4 v[40:43], v[44:45], off offset:32
	s_nop 0
	global_load_dwordx4 v[44:47], v[44:45], off offset:48
	s_waitcnt vmcnt(2)
	v_pk_add_f32 v[32:33], v[32:33], v[34:35]
	v_pk_add_f32 v[36:37], v[36:37], v[38:39]
	s_waitcnt vmcnt(0)
	v_pk_add_f32 v[40:41], v[40:41], v[42:43]
	v_pk_add_f32 v[44:45], v[44:45], v[46:47]
	v_pk_add_f32 v[32:33], v[32:33], v[36:37]
	v_pk_add_f32 v[40:41], v[40:41], v[44:45]
	v_mul_f32_e32 v28, v28, v24
	v_mul_f32_e32 v29, v29, v25
	v_mul_f32_e32 v30, v30, v26
	v_mul_f32_e32 v17, v17, v21
	v_pk_add_f32 v[32:33], v[32:33], v[40:41]
	v_mul_f32_e32 v18, v18, v22
	v_mul_f32_e32 v31, v31, v27
	v_mul_f32_e32 v16, v16, v20
	v_mul_f32_e32 v19, v19, v23
	v_add_f32_e32 v32, v32, v33
	v_fmamk_f32 v32, v32, 0x3a800000, v160
	v_rsq_f32_e32 v33, v32
	s_nop 0
	v_mul_f32_e32 v33, 0xbfb8aa3b, v33
	v_mul_f32_e32 v24, v33, v24
	v_mul_f32_e32 v25, v33, v25
	v_mul_f32_e32 v26, v33, v26
	v_mul_f32_e32 v21, v33, v21
	v_mul_f32_e32 v22, v33, v22
	v_mul_f32_e32 v27, v33, v27
	v_mul_f32_e32 v20, v33, v20
	v_mul_f32_e32 v23, v33, v23
	v_exp_f32_e32 v24, v24
	v_exp_f32_e32 v25, v25
	v_exp_f32_e32 v26, v26
	v_exp_f32_e32 v21, v21
	v_exp_f32_e32 v22, v22
	v_exp_f32_e32 v27, v27
	v_exp_f32_e32 v20, v20
	v_exp_f32_e32 v23, v23
	v_fma_f32 v24, v24, v32, v32
	v_fma_f32 v25, v25, v32, v32
	v_fma_f32 v26, v26, v32, v32
	v_fma_f32 v21, v21, v32, v32
	v_fma_f32 v22, v22, v32, v32
	v_fma_f32 v27, v27, v32, v32
	v_fma_f32 v20, v20, v32, v32
	v_fma_f32 v23, v23, v32, v32
	v_rcp_f32_e32 v24, v24
	v_rcp_f32_e32 v25, v25
	v_rcp_f32_e32 v26, v26
	v_rcp_f32_e32 v21, v21
	v_rcp_f32_e32 v22, v22
	v_rcp_f32_e32 v27, v27
	v_rcp_f32_e32 v20, v20
	v_rcp_f32_e32 v23, v23
	v_mul_f32_e32 v28, v28, v24
	v_mul_f32_e32 v29, v29, v25
	v_mul_f32_e32 v30, v30, v26
	v_mul_f32_e32 v17, v17, v21
	v_mul_f32_e32 v18, v18, v22
	v_mul_f32_e32 v31, v31, v27
	v_mul_f32_e32 v16, v16, v20
	v_mul_f32_e32 v19, v19, v23
	v_cvt_pk_bf16_f32 v19, v18, v19
	v_cvt_pk_bf16_f32 v18, v16, v17
	v_cvt_pk_bf16_f32 v16, v28, v29
	v_cvt_pk_bf16_f32 v17, v30, v31
	v_mad_i64_i32 v[20:21], s[28:29], v48, s53, v[120:121]
	v_lshl_add_u64 v[20:21], v[20:21], 0, s[26:27]
	v_lshl_add_u64 v[20:21], v[20:21], 0, s[8:9]
	v_add_u32_e32 v32, 0xb0, v152
	v_lshl_add_u64 v[20:21], v[20:21], 0, v[136:137]
	v_ashrrev_i32_e32 v33, 31, v32
	global_store_dwordx4 v[20:21], v[16:19], off
	s_nop 1
	v_lshlrev_b64 v[16:17], 6, v[32:33]
	v_lshl_add_u64 v[28:29], s[74:75], 0, v[16:17]
	global_load_dwordx4 v[16:19], v[28:29], off
	global_load_dwordx4 v[20:23], v[28:29], off offset:16
	global_load_dwordx4 v[24:27], v[28:29], off offset:32
	s_nop 0
	global_load_dwordx4 v[28:31], v[28:29], off offset:48
	s_waitcnt vmcnt(2)
	v_pk_add_f32 v[16:17], v[16:17], v[18:19]
	v_pk_add_f32 v[20:21], v[20:21], v[22:23]
	s_waitcnt vmcnt(0)
	v_pk_add_f32 v[24:25], v[24:25], v[26:27]
	v_pk_add_f32 v[28:29], v[28:29], v[30:31]
	v_pk_add_f32 v[16:17], v[16:17], v[20:21]
	v_pk_add_f32 v[24:25], v[24:25], v[28:29]
	v_mul_f32_e32 v12, v12, v8
	v_mul_f32_e32 v13, v13, v9
	v_mul_f32_e32 v14, v14, v10
	v_mul_f32_e32 v1, v1, v5
	v_pk_add_f32 v[16:17], v[16:17], v[24:25]
	v_mul_f32_e32 v2, v2, v6
	v_mul_f32_e32 v15, v15, v11
	v_mul_f32_e32 v0, v0, v4
	v_mul_f32_e32 v3, v3, v7
	v_add_f32_e32 v16, v16, v17
	v_fmamk_f32 v16, v16, 0x3a800000, v160
	v_rsq_f32_e32 v17, v16
	s_nop 0
	v_mul_f32_e32 v17, 0xbfb8aa3b, v17
	v_mul_f32_e32 v8, v17, v8
	v_mul_f32_e32 v9, v17, v9
	v_mul_f32_e32 v10, v17, v10
	v_mul_f32_e32 v5, v17, v5
	v_mul_f32_e32 v6, v17, v6
	v_mul_f32_e32 v11, v17, v11
	v_mul_f32_e32 v4, v17, v4
	v_mul_f32_e32 v7, v17, v7
	v_exp_f32_e32 v8, v8
	v_exp_f32_e32 v9, v9
	v_exp_f32_e32 v10, v10
	v_exp_f32_e32 v5, v5
	v_exp_f32_e32 v6, v6
	v_exp_f32_e32 v11, v11
	v_exp_f32_e32 v4, v4
	v_exp_f32_e32 v7, v7
	v_fma_f32 v8, v8, v16, v16
	v_fma_f32 v9, v9, v16, v16
	v_fma_f32 v10, v10, v16, v16
	v_fma_f32 v5, v5, v16, v16
	v_fma_f32 v6, v6, v16, v16
	v_fma_f32 v11, v11, v16, v16
	v_fma_f32 v4, v4, v16, v16
	v_fma_f32 v7, v7, v16, v16
	v_rcp_f32_e32 v8, v8
	v_rcp_f32_e32 v9, v9
	v_rcp_f32_e32 v10, v10
	v_rcp_f32_e32 v5, v5
	v_rcp_f32_e32 v6, v6
	v_rcp_f32_e32 v11, v11
	v_rcp_f32_e32 v4, v4
	v_rcp_f32_e32 v7, v7
	v_mul_f32_e32 v12, v12, v8
	v_mul_f32_e32 v13, v13, v9
	v_mul_f32_e32 v14, v14, v10
	v_mul_f32_e32 v1, v1, v5
	v_mul_f32_e32 v2, v2, v6
	v_mul_f32_e32 v15, v15, v11
	v_mul_f32_e32 v0, v0, v4
	v_mul_f32_e32 v3, v3, v7
	v_cvt_pk_bf16_f32 v3, v2, v3
	v_cvt_pk_bf16_f32 v2, v0, v1
	v_cvt_pk_bf16_f32 v0, v12, v13
	v_cvt_pk_bf16_f32 v1, v14, v15
	v_mad_i64_i32 v[4:5], s[28:29], v32, s53, v[120:121]
	v_lshl_add_u64 v[4:5], v[4:5], 0, s[26:27]
	v_lshl_add_u64 v[4:5], v[4:5], 0, s[8:9]
	v_lshl_add_u64 v[4:5], v[4:5], 0, v[136:137]
	global_store_dwordx4 v[4:5], v[0:3], off
	s_nop 1
	s_andn2_b64 vcc, exec, s[4:5]
	s_mov_b64 s[4:5], -1
	s_cbranch_vccnz .LBB0_973
	s_branch .LBB0_1007

.LBB0_1135:
	v_ashrrev_i32_e32 v155, 31, v154
	v_lshlrev_b64 v[156:157], 6, v[154:155]
	v_lshl_add_u64 v[156:157], s[74:75], 0, v[156:157]
	global_load_dwordx4 v[166:169], v[156:157], off
	global_load_dwordx4 v[170:173], v[156:157], off offset:16
	global_load_dwordx4 v[174:177], v[156:157], off offset:32
	global_load_dwordx4 v[178:181], v[156:157], off offset:48
	s_lshl_b32 s28, s28, 7
	v_mov_b32_e32 v156, v124
	v_mov_b32_e32 v124, v126
	v_mov_b32_e32 v126, v120
	v_mov_b32_e32 v157, v116
	v_mov_b32_e32 v116, v125
	v_mov_b32_e32 v125, v118
	v_mov_b32_e32 v118, v127
	v_mov_b32_e32 v127, v112
	v_mov_b32_e32 v112, v121
	v_mov_b64_e32 v[120:121], s[72:73]
	s_ashr_i32 s29, s28, 31
	v_mov_b32_e32 v182, v122
	v_mov_b32_e32 v183, v114
	v_mov_b32_e32 v114, v123
	v_mad_i64_i32 v[122:123], s[30:31], v154, s54, v[120:121]
	s_lshl_b64 s[28:29], s[28:29], 1
	v_lshl_add_u64 v[122:123], v[122:123], 0, s[28:29]
	v_lshl_add_u64 v[122:123], v[122:123], 0, s[8:9]
	s_waitcnt vmcnt(2)
	v_pk_add_f32 v[166:167], v[166:167], v[168:169]
	v_pk_add_f32 v[170:171], v[170:171], v[172:173]
	s_waitcnt vmcnt(0)
	v_pk_add_f32 v[174:175], v[174:175], v[176:177]
	v_pk_add_f32 v[178:179], v[178:179], v[180:181]
	v_pk_add_f32 v[166:167], v[166:167], v[170:171]
	v_pk_add_f32 v[174:175], v[174:175], v[178:179]
	v_mul_f32_e32 v116, v116, v117
	v_mul_f32_e32 v124, v124, v125
	v_mul_f32_e32 v118, v118, v119
	v_mul_f32_e32 v126, v126, v127
	v_pk_add_f32 v[166:167], v[166:167], v[174:175]
	v_mul_f32_e32 v156, v156, v157
	v_mul_f32_e32 v112, v112, v113
	v_mul_f32_e32 v182, v182, v183
	v_mul_f32_e32 v114, v114, v115
	v_add_f32_e32 v166, v166, v167
	v_fmamk_f32 v166, v166, 0x3a800000, v163
	v_rsq_f32_e32 v167, v166
	s_nop 0
	v_mul_f32_e32 v167, 0xbfb8aa3b, v167
	v_mul_f32_e32 v117, v167, v117
	v_mul_f32_e32 v125, v167, v125
	v_mul_f32_e32 v119, v167, v119
	v_mul_f32_e32 v127, v167, v127
	v_mul_f32_e32 v157, v167, v157
	v_mul_f32_e32 v113, v167, v113
	v_mul_f32_e32 v183, v167, v183
	v_mul_f32_e32 v115, v167, v115
	v_exp_f32_e32 v117, v117
	v_exp_f32_e32 v125, v125
	v_exp_f32_e32 v119, v119
	v_exp_f32_e32 v127, v127
	v_exp_f32_e32 v157, v157
	v_exp_f32_e32 v113, v113
	v_exp_f32_e32 v183, v183
	v_exp_f32_e32 v115, v115
	v_fma_f32 v117, v117, v166, v166
	v_fma_f32 v125, v125, v166, v166
	v_fma_f32 v119, v119, v166, v166
	v_fma_f32 v127, v127, v166, v166
	v_fma_f32 v157, v157, v166, v166
	v_fma_f32 v113, v113, v166, v166
	v_fma_f32 v183, v183, v166, v166
	v_fma_f32 v115, v115, v166, v166
	v_rcp_f32_e32 v117, v117
	v_rcp_f32_e32 v125, v125
	v_rcp_f32_e32 v119, v119
	v_rcp_f32_e32 v127, v127
	v_rcp_f32_e32 v157, v157
	v_rcp_f32_e32 v113, v113
	v_rcp_f32_e32 v183, v183
	v_rcp_f32_e32 v115, v115
	v_mul_f32_e32 v116, v116, v117
	v_mul_f32_e32 v124, v124, v125
	v_mul_f32_e32 v118, v118, v119
	v_mul_f32_e32 v126, v126, v127
	v_mul_f32_e32 v156, v156, v157
	v_mul_f32_e32 v112, v112, v113
	v_mul_f32_e32 v182, v182, v183
	v_mul_f32_e32 v114, v114, v115
	v_cvt_pk_bf16_f32 v113, v124, v118
	v_cvt_pk_bf16_f32 v115, v182, v114
	v_cvt_pk_bf16_f32 v114, v126, v112
	v_cvt_pk_bf16_f32 v112, v156, v116
	v_or_b32_e32 v126, 16, v154
	v_lshl_add_u64 v[116:117], v[122:123], 0, v[136:137]
	v_ashrrev_i32_e32 v127, 31, v126
	global_store_dwordx4 v[116:117], v[112:115], off
	s_nop 1
	s_nop 1
	v_lshlrev_b64 v[112:113], 6, v[126:127]
	v_lshl_add_u64 v[156:157], s[74:75], 0, v[112:113]
	global_load_dwordx4 v[112:115], v[156:157], off
	global_load_dwordx4 v[116:119], v[156:157], off offset:16
	global_load_dwordx4 v[122:125], v[156:157], off offset:32
	global_load_dwordx4 v[166:169], v[156:157], off offset:48
	s_waitcnt vmcnt(2)
	v_pk_add_f32 v[112:113], v[112:113], v[114:115]
	v_pk_add_f32 v[116:117], v[116:117], v[118:119]
	s_waitcnt vmcnt(0)
	v_pk_add_f32 v[122:123], v[122:123], v[124:125]
	v_pk_add_f32 v[166:167], v[166:167], v[168:169]
	v_pk_add_f32 v[112:113], v[112:113], v[116:117]
	v_pk_add_f32 v[122:123], v[122:123], v[166:167]
	v_mul_f32_e32 v109, v109, v101
	v_mul_f32_e32 v110, v110, v102
	v_mul_f32_e32 v108, v108, v100
	v_mul_f32_e32 v111, v111, v103
	v_pk_add_f32 v[112:113], v[112:113], v[122:123]
	v_mul_f32_e32 v104, v104, v96
	v_mul_f32_e32 v105, v105, v97
	v_mul_f32_e32 v106, v106, v98
	v_mul_f32_e32 v107, v107, v99
	v_add_f32_e32 v112, v112, v113
	v_fmamk_f32 v112, v112, 0x3a800000, v163
	v_rsq_f32_e32 v113, v112
	s_nop 0
	v_mul_f32_e32 v113, 0xbfb8aa3b, v113
	v_mul_f32_e32 v101, v113, v101
	v_mul_f32_e32 v102, v113, v102
	v_mul_f32_e32 v100, v113, v100
	v_mul_f32_e32 v103, v113, v103
	v_mul_f32_e32 v96, v113, v96
	v_mul_f32_e32 v97, v113, v97
	v_mul_f32_e32 v98, v113, v98
	v_mul_f32_e32 v99, v113, v99
	v_exp_f32_e32 v101, v101
	v_exp_f32_e32 v102, v102
	v_exp_f32_e32 v100, v100
	v_exp_f32_e32 v103, v103
	v_exp_f32_e32 v96, v96
	v_exp_f32_e32 v97, v97
	v_exp_f32_e32 v98, v98
	v_exp_f32_e32 v99, v99
	v_fma_f32 v101, v101, v112, v112
	v_fma_f32 v102, v102, v112, v112
	v_fma_f32 v100, v100, v112, v112
	v_fma_f32 v103, v103, v112, v112
	v_fma_f32 v96, v96, v112, v112
	v_fma_f32 v97, v97, v112, v112
	v_fma_f32 v98, v98, v112, v112
	v_fma_f32 v99, v99, v112, v112
	v_rcp_f32_e32 v101, v101
	v_rcp_f32_e32 v102, v102
	v_rcp_f32_e32 v100, v100
	v_rcp_f32_e32 v103, v103
	v_rcp_f32_e32 v96, v96
	v_rcp_f32_e32 v97, v97
	v_rcp_f32_e32 v98, v98
	v_rcp_f32_e32 v99, v99
	v_mul_f32_e32 v109, v109, v101
	v_mul_f32_e32 v110, v110, v102
	v_mul_f32_e32 v108, v108, v100
	v_mul_f32_e32 v111, v111, v103
	v_mul_f32_e32 v104, v104, v96
	v_mul_f32_e32 v105, v105, v97
	v_mul_f32_e32 v106, v106, v98
	v_mul_f32_e32 v107, v107, v99
	v_cvt_pk_bf16_f32 v96, v108, v109
	v_cvt_pk_bf16_f32 v97, v110, v111
	v_cvt_pk_bf16_f32 v98, v104, v105
	v_cvt_pk_bf16_f32 v99, v106, v107
	v_mad_i64_i32 v[112:113], s[30:31], v126, s54, v[120:121]
	v_lshl_add_u64 v[112:113], v[112:113], 0, s[28:29]
	v_lshl_add_u64 v[100:101], v[112:113], 0, s[8:9]
	v_or_b32_e32 v112, 32, v154
	v_lshl_add_u64 v[100:101], v[100:101], 0, v[136:137]
	v_ashrrev_i32_e32 v113, 31, v112
	global_store_dwordx4 v[100:101], v[96:99], off
	s_nop 1
	v_lshlrev_b64 v[96:97], 6, v[112:113]
	v_lshl_add_u64 v[108:109], s[74:75], 0, v[96:97]
	global_load_dwordx4 v[96:99], v[108:109], off
	global_load_dwordx4 v[100:103], v[108:109], off offset:16
	global_load_dwordx4 v[104:107], v[108:109], off offset:32
	s_nop 0
	global_load_dwordx4 v[108:111], v[108:109], off offset:48
	s_waitcnt vmcnt(2)
	v_pk_add_f32 v[96:97], v[96:97], v[98:99]
	v_pk_add_f32 v[100:101], v[100:101], v[102:103]
	s_waitcnt vmcnt(0)
	v_pk_add_f32 v[104:105], v[104:105], v[106:107]
	v_pk_add_f32 v[108:109], v[108:109], v[110:111]
	v_pk_add_f32 v[96:97], v[96:97], v[100:101]
	v_pk_add_f32 v[104:105], v[104:105], v[108:109]
	v_mul_f32_e32 v92, v92, v88
	v_mul_f32_e32 v93, v93, v89
	v_mul_f32_e32 v94, v94, v90
	v_mul_f32_e32 v95, v95, v91
	v_pk_add_f32 v[96:97], v[96:97], v[104:105]
	v_mul_f32_e32 v80, v80, v84
	v_mul_f32_e32 v81, v81, v85
	v_mul_f32_e32 v82, v82, v86
	v_mul_f32_e32 v83, v83, v87
	v_add_f32_e32 v96, v96, v97
	v_fmamk_f32 v96, v96, 0x3a800000, v163
	v_rsq_f32_e32 v97, v96
	s_nop 0
	v_mul_f32_e32 v97, 0xbfb8aa3b, v97
	v_mul_f32_e32 v88, v97, v88
	v_mul_f32_e32 v89, v97, v89
	v_mul_f32_e32 v90, v97, v90
	v_mul_f32_e32 v91, v97, v91
	v_mul_f32_e32 v84, v97, v84
	v_mul_f32_e32 v85, v97, v85
	v_mul_f32_e32 v86, v97, v86
	v_mul_f32_e32 v87, v97, v87
	v_exp_f32_e32 v88, v88
	v_exp_f32_e32 v89, v89
	v_exp_f32_e32 v90, v90
	v_exp_f32_e32 v91, v91
	v_exp_f32_e32 v84, v84
	v_exp_f32_e32 v85, v85
	v_exp_f32_e32 v86, v86
	v_exp_f32_e32 v87, v87
	v_fma_f32 v88, v88, v96, v96
	v_fma_f32 v89, v89, v96, v96
	v_fma_f32 v90, v90, v96, v96
	v_fma_f32 v91, v91, v96, v96
	v_fma_f32 v84, v84, v96, v96
	v_fma_f32 v85, v85, v96, v96
	v_fma_f32 v86, v86, v96, v96
	v_fma_f32 v87, v87, v96, v96
	v_rcp_f32_e32 v88, v88
	v_rcp_f32_e32 v89, v89
	v_rcp_f32_e32 v90, v90
	v_rcp_f32_e32 v91, v91
	v_rcp_f32_e32 v84, v84
	v_rcp_f32_e32 v85, v85
	v_rcp_f32_e32 v86, v86
	v_rcp_f32_e32 v87, v87
	v_mul_f32_e32 v92, v92, v88
	v_mul_f32_e32 v93, v93, v89
	v_mul_f32_e32 v94, v94, v90
	v_mul_f32_e32 v95, v95, v91
	v_mul_f32_e32 v80, v80, v84
	v_mul_f32_e32 v81, v81, v85
	v_mul_f32_e32 v82, v82, v86
	v_mul_f32_e32 v83, v83, v87
	v_cvt_pk_bf16_f32 v83, v82, v83
	v_cvt_pk_bf16_f32 v82, v80, v81
	v_cvt_pk_bf16_f32 v80, v92, v93
	v_cvt_pk_bf16_f32 v81, v94, v95
	v_mad_i64_i32 v[96:97], s[30:31], v112, s54, v[120:121]
	v_lshl_add_u64 v[84:85], v[96:97], 0, s[28:29]
	v_lshl_add_u64 v[84:85], v[84:85], 0, s[8:9]
	v_or_b32_e32 v96, 48, v154
	v_lshl_add_u64 v[84:85], v[84:85], 0, v[136:137]
	v_ashrrev_i32_e32 v97, 31, v96
	global_store_dwordx4 v[84:85], v[80:83], off
	s_nop 1
	v_lshlrev_b64 v[80:81], 6, v[96:97]
	v_lshl_add_u64 v[92:93], s[74:75], 0, v[80:81]
	global_load_dwordx4 v[80:83], v[92:93], off
	global_load_dwordx4 v[84:87], v[92:93], off offset:16
	global_load_dwordx4 v[88:91], v[92:93], off offset:32
	s_nop 0
	global_load_dwordx4 v[92:95], v[92:93], off offset:48
	s_waitcnt vmcnt(2)
	v_pk_add_f32 v[80:81], v[80:81], v[82:83]
	v_pk_add_f32 v[84:85], v[84:85], v[86:87]
	s_waitcnt vmcnt(0)
	v_pk_add_f32 v[88:89], v[88:89], v[90:91]
	v_pk_add_f32 v[92:93], v[92:93], v[94:95]
	v_pk_add_f32 v[80:81], v[80:81], v[84:85]
	v_pk_add_f32 v[88:89], v[88:89], v[92:93]
	v_mul_f32_e32 v76, v76, v72
	v_mul_f32_e32 v77, v77, v73
	v_mul_f32_e32 v78, v78, v74
	v_mul_f32_e32 v65, v65, v69
	v_pk_add_f32 v[80:81], v[80:81], v[88:89]
	v_mul_f32_e32 v66, v66, v70
	v_mul_f32_e32 v79, v79, v75
	v_mul_f32_e32 v64, v64, v68
	v_mul_f32_e32 v67, v67, v71
	v_add_f32_e32 v80, v80, v81
	v_fmamk_f32 v80, v80, 0x3a800000, v163
	v_rsq_f32_e32 v81, v80
	s_nop 0
	v_mul_f32_e32 v81, 0xbfb8aa3b, v81
	v_mul_f32_e32 v72, v81, v72
	v_mul_f32_e32 v73, v81, v73
	v_mul_f32_e32 v74, v81, v74
	v_mul_f32_e32 v69, v81, v69
	v_mul_f32_e32 v70, v81, v70
	v_mul_f32_e32 v75, v81, v75
	v_mul_f32_e32 v68, v81, v68
	v_mul_f32_e32 v71, v81, v71
	v_exp_f32_e32 v72, v72
	v_exp_f32_e32 v73, v73
	v_exp_f32_e32 v74, v74
	v_exp_f32_e32 v69, v69
	v_exp_f32_e32 v70, v70
	v_exp_f32_e32 v75, v75
	v_exp_f32_e32 v68, v68
	v_exp_f32_e32 v71, v71
	v_fma_f32 v72, v72, v80, v80
	v_fma_f32 v73, v73, v80, v80
	v_fma_f32 v74, v74, v80, v80
	v_fma_f32 v69, v69, v80, v80
	v_fma_f32 v70, v70, v80, v80
	v_fma_f32 v75, v75, v80, v80
	v_fma_f32 v68, v68, v80, v80
	v_fma_f32 v71, v71, v80, v80
	v_rcp_f32_e32 v72, v72
	v_rcp_f32_e32 v73, v73
	v_rcp_f32_e32 v74, v74
	v_rcp_f32_e32 v69, v69
	v_rcp_f32_e32 v70, v70
	v_rcp_f32_e32 v75, v75
	v_rcp_f32_e32 v68, v68
	v_rcp_f32_e32 v71, v71
	v_mul_f32_e32 v76, v76, v72
	v_mul_f32_e32 v77, v77, v73
	v_mul_f32_e32 v78, v78, v74
	v_mul_f32_e32 v65, v65, v69
	v_mul_f32_e32 v66, v66, v70
	v_mul_f32_e32 v79, v79, v75
	v_mul_f32_e32 v64, v64, v68
	v_mul_f32_e32 v67, v67, v71
	v_cvt_pk_bf16_f32 v67, v66, v67
	v_cvt_pk_bf16_f32 v66, v64, v65
	v_cvt_pk_bf16_f32 v64, v76, v77
	v_cvt_pk_bf16_f32 v65, v78, v79
	v_mad_i64_i32 v[68:69], s[30:31], v96, s54, v[120:121]
	v_lshl_add_u64 v[68:69], v[68:69], 0, s[28:29]
	v_lshl_add_u64 v[68:69], v[68:69], 0, s[8:9]
	v_add_u32_e32 v80, 0x80, v154
	v_lshl_add_u64 v[68:69], v[68:69], 0, v[136:137]
	v_ashrrev_i32_e32 v81, 31, v80
	global_store_dwordx4 v[68:69], v[64:67], off
	s_nop 1
	v_lshlrev_b64 v[64:65], 6, v[80:81]
	v_lshl_add_u64 v[76:77], s[74:75], 0, v[64:65]
	global_load_dwordx4 v[64:67], v[76:77], off
	global_load_dwordx4 v[68:71], v[76:77], off offset:16
	global_load_dwordx4 v[72:75], v[76:77], off offset:32
	s_nop 0
	global_load_dwordx4 v[76:79], v[76:77], off offset:48
	s_waitcnt vmcnt(2)
	v_pk_add_f32 v[64:65], v[64:65], v[66:67]
	v_pk_add_f32 v[68:69], v[68:69], v[70:71]
	s_waitcnt vmcnt(0)
	v_pk_add_f32 v[72:73], v[72:73], v[74:75]
	v_pk_add_f32 v[76:77], v[76:77], v[78:79]
	v_pk_add_f32 v[64:65], v[64:65], v[68:69]
	v_pk_add_f32 v[72:73], v[72:73], v[76:77]
	v_mul_f32_e32 v60, v60, v56
	v_mul_f32_e32 v61, v61, v57
	v_mul_f32_e32 v62, v62, v58
	v_mul_f32_e32 v49, v49, v53
	v_pk_add_f32 v[64:65], v[64:65], v[72:73]
	v_mul_f32_e32 v50, v50, v54
	v_mul_f32_e32 v63, v63, v59
	v_mul_f32_e32 v48, v48, v52
	v_mul_f32_e32 v51, v51, v55
	v_add_f32_e32 v64, v64, v65
	v_fmamk_f32 v64, v64, 0x3a800000, v163
	v_rsq_f32_e32 v65, v64
	s_nop 0
	v_mul_f32_e32 v65, 0xbfb8aa3b, v65
	v_mul_f32_e32 v56, v65, v56
	v_mul_f32_e32 v57, v65, v57
	v_mul_f32_e32 v58, v65, v58
	v_mul_f32_e32 v53, v65, v53
	v_mul_f32_e32 v54, v65, v54
	v_mul_f32_e32 v59, v65, v59
	v_mul_f32_e32 v52, v65, v52
	v_mul_f32_e32 v55, v65, v55
	v_exp_f32_e32 v56, v56
	v_exp_f32_e32 v57, v57
	v_exp_f32_e32 v58, v58
	v_exp_f32_e32 v53, v53
	v_exp_f32_e32 v54, v54
	v_exp_f32_e32 v59, v59
	v_exp_f32_e32 v52, v52
	v_exp_f32_e32 v55, v55
	v_fma_f32 v56, v56, v64, v64
	v_fma_f32 v57, v57, v64, v64
	v_fma_f32 v58, v58, v64, v64
	v_fma_f32 v53, v53, v64, v64
	v_fma_f32 v54, v54, v64, v64
	v_fma_f32 v59, v59, v64, v64
	v_fma_f32 v52, v52, v64, v64
	v_fma_f32 v55, v55, v64, v64
	v_rcp_f32_e32 v56, v56
	v_rcp_f32_e32 v57, v57
	v_rcp_f32_e32 v58, v58
	v_rcp_f32_e32 v53, v53
	v_rcp_f32_e32 v54, v54
	v_rcp_f32_e32 v59, v59
	v_rcp_f32_e32 v52, v52
	v_rcp_f32_e32 v55, v55
	v_mul_f32_e32 v60, v60, v56
	v_mul_f32_e32 v61, v61, v57
	v_mul_f32_e32 v62, v62, v58
	v_mul_f32_e32 v49, v49, v53
	v_mul_f32_e32 v50, v50, v54
	v_mul_f32_e32 v63, v63, v59
	v_mul_f32_e32 v48, v48, v52
	v_mul_f32_e32 v51, v51, v55
	v_cvt_pk_bf16_f32 v51, v50, v51
	v_cvt_pk_bf16_f32 v50, v48, v49
	v_cvt_pk_bf16_f32 v48, v60, v61
	v_cvt_pk_bf16_f32 v49, v62, v63
	v_mad_i64_i32 v[52:53], s[30:31], v80, s54, v[120:121]
	v_lshl_add_u64 v[52:53], v[52:53], 0, s[28:29]
	v_lshl_add_u64 v[52:53], v[52:53], 0, s[8:9]
	v_add_u32_e32 v64, 0x90, v154
	v_lshl_add_u64 v[52:53], v[52:53], 0, v[136:137]
	v_ashrrev_i32_e32 v65, 31, v64
	global_store_dwordx4 v[52:53], v[48:51], off
	s_nop 1
	v_lshlrev_b64 v[48:49], 6, v[64:65]
	v_lshl_add_u64 v[60:61], s[74:75], 0, v[48:49]
	global_load_dwordx4 v[48:51], v[60:61], off
	global_load_dwordx4 v[52:55], v[60:61], off offset:16
	global_load_dwordx4 v[56:59], v[60:61], off offset:32
	s_nop 0
	global_load_dwordx4 v[60:63], v[60:61], off offset:48
	s_waitcnt vmcnt(2)
	v_pk_add_f32 v[48:49], v[48:49], v[50:51]
	v_pk_add_f32 v[52:53], v[52:53], v[54:55]
	s_waitcnt vmcnt(0)
	v_pk_add_f32 v[56:57], v[56:57], v[58:59]
	v_pk_add_f32 v[60:61], v[60:61], v[62:63]
	v_pk_add_f32 v[48:49], v[48:49], v[52:53]
	v_pk_add_f32 v[56:57], v[56:57], v[60:61]
	v_mul_f32_e32 v44, v44, v40
	v_mul_f32_e32 v45, v45, v41
	v_mul_f32_e32 v46, v46, v42
	v_mul_f32_e32 v33, v33, v37
	v_pk_add_f32 v[48:49], v[48:49], v[56:57]
	v_mul_f32_e32 v34, v34, v38
	v_mul_f32_e32 v47, v47, v43
	v_mul_f32_e32 v32, v32, v36
	v_mul_f32_e32 v35, v35, v39
	v_add_f32_e32 v48, v48, v49
	v_fmamk_f32 v48, v48, 0x3a800000, v163
	v_rsq_f32_e32 v49, v48
	s_nop 0
	v_mul_f32_e32 v49, 0xbfb8aa3b, v49
	v_mul_f32_e32 v40, v49, v40
	v_mul_f32_e32 v41, v49, v41
	v_mul_f32_e32 v42, v49, v42
	v_mul_f32_e32 v37, v49, v37
	v_mul_f32_e32 v38, v49, v38
	v_mul_f32_e32 v43, v49, v43
	v_mul_f32_e32 v36, v49, v36
	v_mul_f32_e32 v39, v49, v39
	v_exp_f32_e32 v40, v40
	v_exp_f32_e32 v41, v41
	v_exp_f32_e32 v42, v42
	v_exp_f32_e32 v37, v37
	v_exp_f32_e32 v38, v38
	v_exp_f32_e32 v43, v43
	v_exp_f32_e32 v36, v36
	v_exp_f32_e32 v39, v39
	v_fma_f32 v40, v40, v48, v48
	v_fma_f32 v41, v41, v48, v48
	v_fma_f32 v42, v42, v48, v48
	v_fma_f32 v37, v37, v48, v48
	v_fma_f32 v38, v38, v48, v48
	v_fma_f32 v43, v43, v48, v48
	v_fma_f32 v36, v36, v48, v48
	v_fma_f32 v39, v39, v48, v48
	v_rcp_f32_e32 v40, v40
	v_rcp_f32_e32 v41, v41
	v_rcp_f32_e32 v42, v42
	v_rcp_f32_e32 v37, v37
	v_rcp_f32_e32 v38, v38
	v_rcp_f32_e32 v43, v43
	v_rcp_f32_e32 v36, v36
	v_rcp_f32_e32 v39, v39
	v_mul_f32_e32 v44, v44, v40
	v_mul_f32_e32 v45, v45, v41
	v_mul_f32_e32 v46, v46, v42
	v_mul_f32_e32 v33, v33, v37
	v_mul_f32_e32 v34, v34, v38
	v_mul_f32_e32 v47, v47, v43
	v_mul_f32_e32 v32, v32, v36
	v_mul_f32_e32 v35, v35, v39
	v_cvt_pk_bf16_f32 v35, v34, v35
	v_cvt_pk_bf16_f32 v34, v32, v33
	v_cvt_pk_bf16_f32 v32, v44, v45
	v_cvt_pk_bf16_f32 v33, v46, v47
	v_mad_i64_i32 v[36:37], s[30:31], v64, s54, v[120:121]
	v_lshl_add_u64 v[36:37], v[36:37], 0, s[28:29]
	v_lshl_add_u64 v[36:37], v[36:37], 0, s[8:9]
	v_add_u32_e32 v48, 0xa0, v154
	v_lshl_add_u64 v[36:37], v[36:37], 0, v[136:137]
	v_ashrrev_i32_e32 v49, 31, v48
	global_store_dwordx4 v[36:37], v[32:35], off
	s_nop 1
	v_lshlrev_b64 v[32:33], 6, v[48:49]
	v_lshl_add_u64 v[44:45], s[74:75], 0, v[32:33]
	global_load_dwordx4 v[32:35], v[44:45], off
	global_load_dwordx4 v[36:39], v[44:45], off offset:16
	global_load_dwordx4 v[40:43], v[44:45], off offset:32
	s_nop 0
	global_load_dwordx4 v[44:47], v[44:45], off offset:48
	s_waitcnt vmcnt(2)
	v_pk_add_f32 v[32:33], v[32:33], v[34:35]
	v_pk_add_f32 v[36:37], v[36:37], v[38:39]
	s_waitcnt vmcnt(0)
	v_pk_add_f32 v[40:41], v[40:41], v[42:43]
	v_pk_add_f32 v[44:45], v[44:45], v[46:47]
	v_pk_add_f32 v[32:33], v[32:33], v[36:37]
	v_pk_add_f32 v[40:41], v[40:41], v[44:45]
	v_mul_f32_e32 v28, v28, v24
	v_mul_f32_e32 v29, v29, v25
	v_mul_f32_e32 v30, v30, v26
	v_mul_f32_e32 v17, v17, v21
	v_pk_add_f32 v[32:33], v[32:33], v[40:41]
	v_mul_f32_e32 v18, v18, v22
	v_mul_f32_e32 v31, v31, v27
	v_mul_f32_e32 v16, v16, v20
	v_mul_f32_e32 v19, v19, v23
	v_add_f32_e32 v32, v32, v33
	v_fmamk_f32 v32, v32, 0x3a800000, v163
	v_rsq_f32_e32 v33, v32
	s_nop 0
	v_mul_f32_e32 v33, 0xbfb8aa3b, v33
	v_mul_f32_e32 v24, v33, v24
	v_mul_f32_e32 v25, v33, v25
	v_mul_f32_e32 v26, v33, v26
	v_mul_f32_e32 v21, v33, v21
	v_mul_f32_e32 v22, v33, v22
	v_mul_f32_e32 v27, v33, v27
	v_mul_f32_e32 v20, v33, v20
	v_mul_f32_e32 v23, v33, v23
	v_exp_f32_e32 v24, v24
	v_exp_f32_e32 v25, v25
	v_exp_f32_e32 v26, v26
	v_exp_f32_e32 v21, v21
	v_exp_f32_e32 v22, v22
	v_exp_f32_e32 v27, v27
	v_exp_f32_e32 v20, v20
	v_exp_f32_e32 v23, v23
	v_fma_f32 v24, v24, v32, v32
	v_fma_f32 v25, v25, v32, v32
	v_fma_f32 v26, v26, v32, v32
	v_fma_f32 v21, v21, v32, v32
	v_fma_f32 v22, v22, v32, v32
	v_fma_f32 v27, v27, v32, v32
	v_fma_f32 v20, v20, v32, v32
	v_fma_f32 v23, v23, v32, v32
	v_rcp_f32_e32 v24, v24
	v_rcp_f32_e32 v25, v25
	v_rcp_f32_e32 v26, v26
	v_rcp_f32_e32 v21, v21
	v_rcp_f32_e32 v22, v22
	v_rcp_f32_e32 v27, v27
	v_rcp_f32_e32 v20, v20
	v_rcp_f32_e32 v23, v23
	v_mul_f32_e32 v28, v28, v24
	v_mul_f32_e32 v29, v29, v25
	v_mul_f32_e32 v30, v30, v26
	v_mul_f32_e32 v17, v17, v21
	v_mul_f32_e32 v18, v18, v22
	v_mul_f32_e32 v31, v31, v27
	v_mul_f32_e32 v16, v16, v20
	v_mul_f32_e32 v19, v19, v23
	v_cvt_pk_bf16_f32 v19, v18, v19
	v_cvt_pk_bf16_f32 v18, v16, v17
	v_cvt_pk_bf16_f32 v16, v28, v29
	v_cvt_pk_bf16_f32 v17, v30, v31
	v_mad_i64_i32 v[20:21], s[30:31], v48, s54, v[120:121]
	v_lshl_add_u64 v[20:21], v[20:21], 0, s[28:29]
	v_lshl_add_u64 v[20:21], v[20:21], 0, s[8:9]
	v_add_u32_e32 v32, 0xb0, v154
	v_lshl_add_u64 v[20:21], v[20:21], 0, v[136:137]
	v_ashrrev_i32_e32 v33, 31, v32
	global_store_dwordx4 v[20:21], v[16:19], off
	s_nop 1
	v_lshlrev_b64 v[16:17], 6, v[32:33]
	v_lshl_add_u64 v[28:29], s[74:75], 0, v[16:17]
	global_load_dwordx4 v[16:19], v[28:29], off
	global_load_dwordx4 v[20:23], v[28:29], off offset:16
	global_load_dwordx4 v[24:27], v[28:29], off offset:32
	s_nop 0
	global_load_dwordx4 v[28:31], v[28:29], off offset:48
	s_waitcnt vmcnt(2)
	v_pk_add_f32 v[16:17], v[16:17], v[18:19]
	v_pk_add_f32 v[20:21], v[20:21], v[22:23]
	s_waitcnt vmcnt(0)
	v_pk_add_f32 v[24:25], v[24:25], v[26:27]
	v_pk_add_f32 v[28:29], v[28:29], v[30:31]
	v_pk_add_f32 v[16:17], v[16:17], v[20:21]
	v_pk_add_f32 v[24:25], v[24:25], v[28:29]
	v_mul_f32_e32 v12, v12, v8
	v_mul_f32_e32 v13, v13, v9
	v_mul_f32_e32 v14, v14, v10
	v_mul_f32_e32 v1, v1, v5
	v_pk_add_f32 v[16:17], v[16:17], v[24:25]
	v_mul_f32_e32 v2, v2, v6
	v_mul_f32_e32 v15, v15, v11
	v_mul_f32_e32 v0, v0, v4
	v_mul_f32_e32 v3, v3, v7
	v_add_f32_e32 v16, v16, v17
	v_fmamk_f32 v16, v16, 0x3a800000, v163
	v_rsq_f32_e32 v17, v16
	s_nop 0
	v_mul_f32_e32 v17, 0xbfb8aa3b, v17
	v_mul_f32_e32 v8, v17, v8
	v_mul_f32_e32 v9, v17, v9
	v_mul_f32_e32 v10, v17, v10
	v_mul_f32_e32 v5, v17, v5
	v_mul_f32_e32 v6, v17, v6
	v_mul_f32_e32 v11, v17, v11
	v_mul_f32_e32 v4, v17, v4
	v_mul_f32_e32 v7, v17, v7
	v_exp_f32_e32 v8, v8
	v_exp_f32_e32 v9, v9
	v_exp_f32_e32 v10, v10
	v_exp_f32_e32 v5, v5
	v_exp_f32_e32 v6, v6
	v_exp_f32_e32 v11, v11
	v_exp_f32_e32 v4, v4
	v_exp_f32_e32 v7, v7
	v_fma_f32 v8, v8, v16, v16
	v_fma_f32 v9, v9, v16, v16
	v_fma_f32 v10, v10, v16, v16
	v_fma_f32 v5, v5, v16, v16
	v_fma_f32 v6, v6, v16, v16
	v_fma_f32 v11, v11, v16, v16
	v_fma_f32 v4, v4, v16, v16
	v_fma_f32 v7, v7, v16, v16
	v_rcp_f32_e32 v8, v8
	v_rcp_f32_e32 v9, v9
	v_rcp_f32_e32 v10, v10
	v_rcp_f32_e32 v5, v5
	v_rcp_f32_e32 v6, v6
	v_rcp_f32_e32 v11, v11
	v_rcp_f32_e32 v4, v4
	v_rcp_f32_e32 v7, v7
	v_mul_f32_e32 v12, v12, v8
	v_mul_f32_e32 v13, v13, v9
	v_mul_f32_e32 v14, v14, v10
	v_mul_f32_e32 v1, v1, v5
	v_mul_f32_e32 v2, v2, v6
	v_mul_f32_e32 v15, v15, v11
	v_mul_f32_e32 v0, v0, v4
	v_mul_f32_e32 v3, v3, v7
	v_cvt_pk_bf16_f32 v3, v2, v3
	v_cvt_pk_bf16_f32 v2, v0, v1
	v_cvt_pk_bf16_f32 v0, v12, v13
	v_cvt_pk_bf16_f32 v1, v14, v15
	v_mad_i64_i32 v[4:5], s[30:31], v32, s54, v[120:121]
	v_lshl_add_u64 v[4:5], v[4:5], 0, s[28:29]
	v_lshl_add_u64 v[4:5], v[4:5], 0, s[8:9]
	v_lshl_add_u64 v[4:5], v[4:5], 0, v[136:137]
	global_store_dwordx4 v[4:5], v[0:3], off
	s_nop 1
	s_andn2_b64 vcc, exec, s[4:5]
	s_mov_b64 s[4:5], -1
	s_cbranch_vccnz .LBB0_1127
	s_branch .LBB0_1161
